# same fold with each site's byte count kept a multiple of 8 (one removed op replaced by s_nop 0)
# speedup vs baseline: 1.0017x; 1.0017x over previous
; #define LAS __attribute__((address_space(3)))
; __device__ __forceinline__ unsigned pk2(float lo, float hi) { return pg8::pkbf(lo, hi); }
; __device__ __forceinline__ float fexp2(float x) { return __builtin_amdgcn_exp2f(x); }
; #define SCHED_FENCE() __builtin_amdgcn_sched_barrier(0)
; #define PV_LOAD(dst, i) do { _Pragma("unroll") for (int d = 0; d < ND; ++d) { LAS const unsigned char* vp = vb + (16 * (i)) * VRB + d * 64; dst[2 * d] = tr_read(vp); dst[2 * d + 1] = tr_read(vp + 8 * VRB); } } while (0)
; #define PV_MMA(src, i) do { _Pragma("unroll") for (int d = 0; d < ND; ++d) { const bf16x8 vf = __builtin_shufflevector(src[2 * d], src[2 * d + 1], 0, 1, 2, 3, 4, 5, 6, 7); o[d] = MFMA32(vf, pf[i], o[d]); } } while (0)
; template <int DV, bool MASK>
; __device__ __forceinline__ void attn_softmax(f32x16 (&p)[2], f32x16 (&o)[DV / 32], float& m, float& l, float cs, int hi, int dq) {
;     ...
;     float ls0 = 0.f, ls1 = 0.f, ls2 = 0.f, ls3 = 0.f;
; #pragma unroll
;     for (int kvb = 0; kvb < 2; ++kvb)
; #pragma unroll
;         for (int e = 0; e < 16; e += 4) {
;             const float e0 = fexp2(fmaf(p[kvb][e], cs, -m)), e1 = fexp2(fmaf(p[kvb][e + 1], cs, -m)), e2 = fexp2(fmaf(p[kvb][e + 2], cs, -m)), e3 = fexp2(fmaf(p[kvb][e + 3], cs, -m));
;             p[kvb][e] = e0; p[kvb][e + 1] = e1; p[kvb][e + 2] = e2; p[kvb][e + 3] = e3; ls0 += e0; ls1 += e1; ls2 += e2; ls3 += e3; }
;     l += (ls0 + ls1) + (ls2 + ls3);
; }
; template <int DV, int VRB>
; __device__ __forceinline__ void attn_pv(LAS const unsigned char* Vt, const f32x16 (&p)[2], f32x16 (&o)[DV / 32], int vtb) {
;     constexpr int ND = DV / 32;
;     LAS const unsigned char* vb = Vt + vtb;
;     bf16x8 pf[4];
; #pragma unroll
;     for (int i = 0; i < 4; ++i) { const int kvb = i >> 1, s = i & 1;
;         v4u pw; pw.x = pk2(p[kvb][8 * s + 0], p[kvb][8 * s + 1]); pw.y = pk2(p[kvb][8 * s + 2], p[kvb][8 * s + 3]); pw.z = pk2(p[kvb][8 * s + 4], p[kvb][8 * s + 5]); pw.w = pk2(p[kvb][8 * s + 6], p[kvb][8 * s + 7]);
;         pf[i] = __builtin_bit_cast(bf16x8, pw); }
;     s16x4 va[2 * ND], vbq[2 * ND];
;     ...
;     PV_LOAD(va, 0); SCHED_FENCE();
;     PV_LOAD(vbq, 1); PV_MMA(va, 0); SCHED_FENCE();
;     PV_LOAD(va, 2); PV_MMA(vbq, 1); SCHED_FENCE();
;     PV_LOAD(vbq, 3); PV_MMA(va, 2); SCHED_FENCE();
.LBB0_836:
	v_add_f32_e32 v154, 0, v154
	v_add_f32_e32 v155, 0, v155
	v_add_f32_e32 v162, 0, v162
	v_add_f32_e32 v163, 0, v163
	v_add_f32_e32 v154, v164, v154
	v_add_f32_e32 v155, v166, v155
	v_add_f32_e32 v162, v167, v162
	v_add_f32_e32 v163, v168, v163
	v_add_f32_e32 v154, v169, v154
	v_add_f32_e32 v155, v181, v155
	v_add_f32_e32 v162, v182, v162
	v_add_f32_e32 v163, v183, v163
	v_add_f32_e32 v154, v196, v154
	v_add_f32_e32 v155, v197, v155
	v_add_f32_e32 v162, v198, v162
	v_add_f32_e32 v163, v199, v163
	v_add_f32_e32 v154, v200, v154
	v_add_f32_e32 v155, v201, v155
	v_add_f32_e32 v162, v202, v162
	v_add_f32_e32 v163, v203, v163
	v_add_f32_e32 v154, v204, v154
	v_add_f32_e32 v155, v205, v155
	v_add_f32_e32 v162, v206, v162
	v_add_f32_e32 v163, v207, v163
	v_add_f32_e32 v154, v208, v154
	v_add_f32_e32 v155, v209, v155
	v_add_f32_e32 v162, v210, v162
	v_add_f32_e32 v163, v211, v163
	v_add_f32_e32 v154, v212, v154
	v_add_f32_e32 v155, v213, v155
	v_add_f32_e32 v162, v214, v162
	v_add_f32_e32 v163, v215, v163
	v_add_f32_e32 v154, v154, v155
	v_add_f32_e32 v155, v162, v163
	v_fmamk_f32 v98, v98, 0x3e38aa3b, v147
	v_add_f32_e32 v154, v154, v155
	v_exp_f32_e32 v155, v98
	v_fmamk_f32 v98, v99, 0x3e38aa3b, v147
	v_fmamk_f32 v82, v82, 0x3e38aa3b, v147
	v_exp_f32_e32 v162, v98
	v_fmamk_f32 v98, v100, 0x3e38aa3b, v147
	v_exp_f32_e32 v201, v82
	v_fmamk_f32 v82, v83, 0x3e38aa3b, v147
	v_exp_f32_e32 v163, v98
	v_fmamk_f32 v98, v101, 0x3e38aa3b, v147
	v_exp_f32_e32 v202, v82
	v_fmamk_f32 v82, v84, 0x3e38aa3b, v147
	v_exp_f32_e32 v164, v98
	v_fmamk_f32 v98, v102, 0x3e38aa3b, v147
	v_exp_f32_e32 v203, v82
	v_fmamk_f32 v82, v85, 0x3e38aa3b, v147
	v_exp_f32_e32 v166, v98
	v_fmamk_f32 v98, v103, 0x3e38aa3b, v147
	v_exp_f32_e32 v204, v82
	v_fmamk_f32 v82, v86, 0x3e38aa3b, v147
	v_exp_f32_e32 v167, v98
	v_fmamk_f32 v98, v104, 0x3e38aa3b, v147
	v_exp_f32_e32 v205, v82
	v_fmamk_f32 v82, v87, 0x3e38aa3b, v147
	v_exp_f32_e32 v168, v98
	v_fmamk_f32 v98, v105, 0x3e38aa3b, v147
	v_exp_f32_e32 v206, v82
	v_fmamk_f32 v82, v88, 0x3e38aa3b, v147
	v_exp_f32_e32 v169, v98
	v_fmamk_f32 v98, v106, 0x3e38aa3b, v147
	v_exp_f32_e32 v207, v82
	v_fmamk_f32 v82, v89, 0x3e38aa3b, v147
	v_exp_f32_e32 v181, v98
	v_fmamk_f32 v98, v107, 0x3e38aa3b, v147
	v_exp_f32_e32 v208, v82
	v_fmamk_f32 v82, v90, 0x3e38aa3b, v147
	v_exp_f32_e32 v182, v98
	v_fmamk_f32 v98, v108, 0x3e38aa3b, v147
	v_exp_f32_e32 v209, v82
	v_fmamk_f32 v82, v91, 0x3e38aa3b, v147
	v_exp_f32_e32 v183, v98
	v_fmamk_f32 v98, v109, 0x3e38aa3b, v147
	v_exp_f32_e32 v210, v82
	v_fmamk_f32 v82, v92, 0x3e38aa3b, v147
	v_exp_f32_e32 v196, v98
	v_fmamk_f32 v98, v110, 0x3e38aa3b, v147
	v_exp_f32_e32 v211, v82
	v_fmamk_f32 v82, v93, 0x3e38aa3b, v147
	v_exp_f32_e32 v197, v98
	v_fmamk_f32 v98, v111, 0x3e38aa3b, v147
	v_exp_f32_e32 v212, v82
	v_fmamk_f32 v82, v94, 0x3e38aa3b, v147
	v_exp_f32_e32 v198, v98
	v_fmamk_f32 v98, v112, 0x3e38aa3b, v147
	v_exp_f32_e32 v213, v82
	v_fmamk_f32 v82, v95, 0x3e38aa3b, v147
	v_exp_f32_e32 v199, v98
	v_fmamk_f32 v98, v113, 0x3e38aa3b, v147
	v_exp_f32_e32 v214, v82
	v_fmamk_f32 v82, v96, 0x3e38aa3b, v147
	v_exp_f32_e32 v200, v98
	v_exp_f32_e32 v215, v82
	v_fmamk_f32 v82, v97, 0x3e38aa3b, v147
	ds_read_b64_tr_b16 v[94:95], v179 offset:30720
	ds_read_b64_tr_b16 v[96:97], v179 offset:32256
	ds_read_b64_tr_b16 v[100:101], v179 offset:32320
	ds_read_b64_tr_b16 v[98:99], v179 offset:30784
	v_exp_f32_e32 v216, v82
	v_cndmask_b32_e64 v150, v150, 1.0, s[2:3]
	v_fmac_f32_e32 v154, v170, v150
	v_cvt_pk_bf16_f32 v82, v155, v162
	v_cvt_pk_bf16_f32 v83, v163, v164
	v_cvt_pk_bf16_f32 v84, v166, v167
	v_cvt_pk_bf16_f32 v85, v168, v169
	v_cvt_pk_bf16_f32 v86, v181, v182
	v_cvt_pk_bf16_f32 v87, v183, v196
	v_cvt_pk_bf16_f32 v88, v197, v198
	v_cvt_pk_bf16_f32 v89, v199, v200
	v_cvt_pk_bf16_f32 v90, v201, v202
	v_cvt_pk_bf16_f32 v91, v203, v204
	v_cvt_pk_bf16_f32 v92, v205, v206
	v_cvt_pk_bf16_f32 v93, v207, v208
	v_cvt_pk_bf16_f32 v102, v209, v210
	v_cvt_pk_bf16_f32 v103, v211, v212
	v_cvt_pk_bf16_f32 v104, v213, v214
	v_cvt_pk_bf16_f32 v105, v215, v216
	s_waitcnt lgkmcnt(2)
; #define LAS __attribute__((address_space(3)))
; template <int DQK, int KSB>
; __device__ __forceinline__ void attn_scores(LAS const unsigned char* Kt, const bf16x8 (&qf)[DQK / 16], f32x16 (&p)[2], int r32, int hi) {
;     constexpr int NK = DQK / 16;
;     LAS const unsigned char* kp = Kt + r32 * KSB + hi * 16;
;     f32x16 p0, p1;
; #pragma unroll
;     for (int e = 0; e < 16; ++e) { p0[e] = 0.f; p1[e] = 0.f; }
;     bf16x8 kr[3][2];
;     ...
;     QK_LOAD(0); QK_LOAD(1); SCHED_FENCE();
; #pragma unroll
;     for (int ks = 0; ks < NK; ++ks) {
;         if (ks + 2 < NK) QK_LOAD(ks + 2);
;         p0 = MFMA32(kr[ks % 3][0], qf[ks], p0); p1 = MFMA32(kr[ks % 3][1], qf[ks], p1); SCHED_FENCE();
;     }
;     ...
;     p[0] = p0; p[1] = p1;
; }
; template <int DV, bool MASK>
; __device__ __forceinline__ void attn_softmax(f32x16 (&p)[2], f32x16 (&o)[DV / 32], float& m, float& l, float cs, int hi, int dq) {
;     if (MASK) { if (__builtin_amdgcn_readfirstlane(dq) != NO_MASK) {
; #pragma unroll
;         for (int kvb = 0; kvb < 2; ++kvb)
; #pragma unroll
;             for (int e = 0; e < 16; ++e) { const int rel = dq + 32 * kvb + (e & 3) + 8 * (e >> 2) + 4 * hi; if (rel > 128 || rel < -128) p[kvb][e] = -INFINITY; } } }
;     float mx;
;     {
;         float a0 = fmaxf(fmaxf(p[0][0], p[0][1]), p[0][2]), a1 = fmaxf(fmaxf(p[0][8], p[0][9]), p[0][10]), a2 = fmaxf(fmaxf(p[1][0], p[1][1]), p[1][2]), a3 = fmaxf(fmaxf(p[1][8], p[1][9]), p[1][10]);
;         a0 = fmaxf(fmaxf(a0, p[0][3]), p[0][4]); a1 = fmaxf(fmaxf(a1, p[0][11]), p[0][12]); a2 = fmaxf(fmaxf(a2, p[1][3]), p[1][4]); a3 = fmaxf(fmaxf(a3, p[1][11]), p[1][12]);
;         a0 = fmaxf(fmaxf(a0, p[0][5]), p[0][6]); a1 = fmaxf(fmaxf(a1, p[0][13]), p[0][14]); a2 = fmaxf(fmaxf(a2, p[1][5]), p[1][6]); a3 = fmaxf(fmaxf(a3, p[1][13]), p[1][14]);
;         a0 = fmaxf(a0, p[0][7]); a1 = fmaxf(a1, p[0][15]); a2 = fmaxf(a2, p[1][7]); a3 = fmaxf(a3, p[1][15]);
;         mx = fmaxf(fmaxf(a0, a1), fmaxf(a2, a3));
; template <int DV, int VRB>
; __device__ __forceinline__ void attn_pv(LAS const unsigned char* Vt, const f32x16 (&p)[2], f32x16 (&o)[DV / 32], int vtb) {
;     ...
;     PV_LOAD(va, 0); SCHED_FENCE();
;     PV_LOAD(vbq, 1); PV_MMA(va, 0); SCHED_FENCE();
;     PV_LOAD(va, 2); PV_MMA(vbq, 1); SCHED_FENCE();
;     PV_LOAD(vbq, 3); PV_MMA(va, 2); SCHED_FENCE();
;     PV_MMA(vbq, 3); SCHED_FENCE();
	v_mfma_f32_32x32x16_bf16 v[50:65], v[94:97], v[82:85], v[50:65]
	ds_read_b64_tr_b16 v[94:95], v179 offset:33792
	ds_read_b64_tr_b16 v[96:97], v179 offset:35328
	ds_read_b64_tr_b16 v[108:109], v179 offset:35392
	ds_read_b64_tr_b16 v[106:107], v179 offset:33856
	s_waitcnt lgkmcnt(4)
	v_mfma_f32_32x32x16_bf16 v[2:17], v[98:101], v[82:85], v[2:17]
	s_waitcnt lgkmcnt(2)
	v_mfma_f32_32x32x16_bf16 v[50:65], v[94:97], v[86:89], v[50:65]
	ds_read_b64_tr_b16 v[82:83], v179 offset:36864
	ds_read_b64_tr_b16 v[84:85], v179 offset:38400
	ds_read_b64_tr_b16 v[96:97], v179 offset:38464
	ds_read_b64_tr_b16 v[94:95], v179 offset:36928
	s_waitcnt lgkmcnt(4)
	v_mfma_f32_32x32x16_bf16 v[2:17], v[106:109], v[86:89], v[2:17]
	s_waitcnt lgkmcnt(2)
	v_mfma_f32_32x32x16_bf16 v[50:65], v[82:85], v[90:93], v[50:65]
	ds_read_b64_tr_b16 v[82:83], v179 offset:39936
	ds_read_b64_tr_b16 v[84:85], v179 offset:41472
	ds_read_b64_tr_b16 v[88:89], v179 offset:41536
	ds_read_b64_tr_b16 v[86:87], v179 offset:40000
	s_waitcnt lgkmcnt(4)
	v_mfma_f32_32x32x16_bf16 v[2:17], v[94:97], v[90:93], v[2:17]
	s_waitcnt lgkmcnt(2)
	v_mfma_f32_32x32x16_bf16 v[50:65], v[82:85], v[102:105], v[50:65]
	s_waitcnt lgkmcnt(0)
	v_mfma_f32_32x32x16_bf16 v[2:17], v[86:89], v[102:105], v[2:17]
	ds_read_b128 v[82:85], v145 offset:21504
	ds_read_b128 v[186:189], v145 offset:21536
	ds_read_b128 v[86:89], v145 offset:26112
	ds_read_b128 v[218:221], v145 offset:26144
	s_waitcnt lgkmcnt(3)
	v_mfma_f32_32x32x16_bf16 v[98:113], v[82:85], v[114:117], 0
	ds_read_b128 v[222:225], v145 offset:21568
	ds_read_b128 v[226:229], v145 offset:26176
	s_waitcnt lgkmcnt(3)
	v_mfma_f32_32x32x16_bf16 v[82:97], v[86:89], v[114:117], 0
	v_mfma_f32_32x32x16_bf16 v[98:113], v[186:189], v[26:29], v[98:113]
	ds_read_b128 v[186:189], v145 offset:21600
	ds_read_b128 v[240:243], v145 offset:26208
	s_waitcnt lgkmcnt(4)
	v_mfma_f32_32x32x16_bf16 v[82:97], v[218:221], v[26:29], v[82:97]
	s_waitcnt lgkmcnt(3)
	v_mfma_f32_32x32x16_bf16 v[98:113], v[222:225], v[22:25], v[98:113]
	s_waitcnt lgkmcnt(2)
	v_mfma_f32_32x32x16_bf16 v[82:97], v[226:229], v[22:25], v[82:97]
	s_waitcnt lgkmcnt(1)
	v_mfma_f32_32x32x16_bf16 v[98:113], v[186:189], v[18:21], v[98:113]
	s_waitcnt lgkmcnt(0)
	v_mfma_f32_32x32x16_bf16 v[82:97], v[240:243], v[18:21], v[82:97]
	s_nop 10
	v_max_f32_e32 v150, v98, v99
	v_max_f32_e32 v188, v90, v91
	v_max_f32_e32 v186, v106, v107
	v_max3_f32 v187, v82, v83, v84
	v_max3_f32 v188, v188, v92, v93
	v_max3_f32 v150, v150, v100, v101
	v_max3_f32 v186, v186, v108, v109
	v_max3_f32 v187, v187, v85, v86
	v_max3_f32 v188, v188, v94, v95
	v_max3_f32 v150, v150, v102, v103
	v_max3_f32 v186, v186, v110, v111
	v_max3_f32 v187, v187, v87, v88
	v_max3_f32 v188, v188, v96, v97
	v_max3_f32 v150, v150, v104, v105
	v_max3_f32 v186, v186, v112, v113
	v_max3_f32 v187, v187, v89, v188
	v_max3_f32 v150, v150, v186, v187
	v_mov_b32_e32 v186, v150
	s_nop 1
	v_permlane32_swap_b32_e32 v150, v186
	v_max_f32_e32 v150, v150, v186
	v_mul_f32_e32 v150, 0x3e38aa3b, v150
	s_nop 0
	v_max_f32_e32 v217, v151, v150
	v_sub_f32_e32 v150, v217, v151
	v_cmp_lt_f32_e32 vcc, s34, v150
	s_cbranch_vccz .LBB0_838
	v_sub_f32_e32 v150, v151, v217
	v_exp_f32_e32 v150, v150
	s_nop 0
	v_mul_f32_e32 v154, v154, v150
	v_pk_mul_f32 v[80:81], v[80:81], v[150:151] op_sel_hi:[1,0]
	v_pk_mul_f32 v[78:79], v[78:79], v[150:151] op_sel_hi:[1,0]
	v_pk_mul_f32 v[76:77], v[76:77], v[150:151] op_sel_hi:[1,0]
	v_pk_mul_f32 v[74:75], v[74:75], v[150:151] op_sel_hi:[1,0]
	v_pk_mul_f32 v[72:73], v[72:73], v[150:151] op_sel_hi:[1,0]
	v_pk_mul_f32 v[70:71], v[70:71], v[150:151] op_sel_hi:[1,0]
	v_pk_mul_f32 v[68:69], v[68:69], v[150:151] op_sel_hi:[1,0]
	v_pk_mul_f32 v[66:67], v[66:67], v[150:151] op_sel_hi:[1,0]
	v_pk_mul_f32 v[48:49], v[48:49], v[150:151] op_sel_hi:[1,0]
	v_pk_mul_f32 v[46:47], v[46:47], v[150:151] op_sel_hi:[1,0]
	v_pk_mul_f32 v[44:45], v[44:45], v[150:151] op_sel_hi:[1,0]
	v_pk_mul_f32 v[42:43], v[42:43], v[150:151] op_sel_hi:[1,0]
	v_pk_mul_f32 v[40:41], v[40:41], v[150:151] op_sel_hi:[1,0]
	v_pk_mul_f32 v[38:39], v[38:39], v[150:151] op_sel_hi:[1,0]
	v_pk_mul_f32 v[36:37], v[36:37], v[150:151] op_sel_hi:[1,0]
	v_pk_mul_f32 v[34:35], v[34:35], v[150:151] op_sel_hi:[1,0]
	v_xor_b32_e32 v150, 0x80000000, v217
	v_mov_b32_e32 v151, v217
	s_branch .LBB0_839

; #define LAS __attribute__((address_space(3)))
; __device__ __forceinline__ unsigned pk2(float lo, float hi) { return pg8::pkbf(lo, hi); }
; __device__ __forceinline__ float fexp2(float x) { return __builtin_amdgcn_exp2f(x); }
; #define SCHED_FENCE() __builtin_amdgcn_sched_barrier(0)
; #define PV_LOAD(dst, i) do { _Pragma("unroll") for (int d = 0; d < ND; ++d) { LAS const unsigned char* vp = vb + (16 * (i)) * VRB + d * 64; dst[2 * d] = tr_read(vp); dst[2 * d + 1] = tr_read(vp + 8 * VRB); } } while (0)
; template <int DV, bool MASK>
; __device__ __forceinline__ void attn_softmax(f32x16 (&p)[2], f32x16 (&o)[DV / 32], float& m, float& l, float cs, int hi, int dq) {
;     ...
;     float ls0 = 0.f, ls1 = 0.f, ls2 = 0.f, ls3 = 0.f;
; #pragma unroll
;     for (int kvb = 0; kvb < 2; ++kvb)
; #pragma unroll
;         for (int e = 0; e < 16; e += 4) {
;             const float e0 = fexp2(fmaf(p[kvb][e], cs, -m)), e1 = fexp2(fmaf(p[kvb][e + 1], cs, -m)), e2 = fexp2(fmaf(p[kvb][e + 2], cs, -m)), e3 = fexp2(fmaf(p[kvb][e + 3], cs, -m));
;             p[kvb][e] = e0; p[kvb][e + 1] = e1; p[kvb][e + 2] = e2; p[kvb][e + 3] = e3; ls0 += e0; ls1 += e1; ls2 += e2; ls3 += e3; }
;     l += (ls0 + ls1) + (ls2 + ls3);
; }
; template <int DV, int VRB>
; __device__ __forceinline__ void attn_pv(LAS const unsigned char* Vt, const f32x16 (&p)[2], f32x16 (&o)[DV / 32], int vtb) {
;     constexpr int ND = DV / 32;
;     LAS const unsigned char* vb = Vt + vtb;
;     bf16x8 pf[4];
; #pragma unroll
;     for (int i = 0; i < 4; ++i) { const int kvb = i >> 1, s = i & 1;
;         v4u pw; pw.x = pk2(p[kvb][8 * s + 0], p[kvb][8 * s + 1]); pw.y = pk2(p[kvb][8 * s + 2], p[kvb][8 * s + 3]); pw.z = pk2(p[kvb][8 * s + 4], p[kvb][8 * s + 5]); pw.w = pk2(p[kvb][8 * s + 6], p[kvb][8 * s + 7]);
;         pf[i] = __builtin_bit_cast(bf16x8, pw); }
;     s16x4 va[2 * ND], vbq[2 * ND];
;     ...
;     PV_LOAD(va, 0); SCHED_FENCE();
;     PV_LOAD(vbq, 1); PV_MMA(va, 0); SCHED_FENCE();
;     PV_LOAD(va, 2); PV_MMA(vbq, 1); SCHED_FENCE();
;     PV_LOAD(vbq, 3); PV_MMA(va, 2); SCHED_FENCE();
;     PV_MMA(vbq, 3); SCHED_FENCE();
; __device__ __forceinline__ void swa_unit(const bf16* Z, const float* sink  , bf16* Y, int b, int g, int blk, int cblk, LAS unsigned char* L, int tid) {
;     ...
;         if (more) SWA_STORE((t + 1) & 1);
;         __syncthreads();
.LBB0_839:
	v_add_f32_e32 v155, 0, v155
	v_add_f32_e32 v162, 0, v162
	v_add_f32_e32 v163, 0, v163
	v_add_f32_e32 v164, 0, v164
	v_add_f32_e32 v155, v166, v155
	v_add_f32_e32 v162, v167, v162
	v_add_f32_e32 v163, v168, v163
	v_add_f32_e32 v164, v169, v164
	v_add_f32_e32 v155, v181, v155
	v_add_f32_e32 v162, v182, v162
	v_add_f32_e32 v163, v183, v163
	v_add_f32_e32 v164, v196, v164
	v_add_f32_e32 v155, v197, v155
	v_add_f32_e32 v162, v198, v162
	v_add_f32_e32 v163, v199, v163
	v_add_f32_e32 v164, v200, v164
	v_add_f32_e32 v155, v201, v155
	v_add_f32_e32 v162, v202, v162
	v_add_f32_e32 v163, v203, v163
	v_add_f32_e32 v164, v204, v164
	v_add_f32_e32 v155, v205, v155
	v_add_f32_e32 v162, v206, v162
	v_add_f32_e32 v163, v207, v163
	v_add_f32_e32 v164, v208, v164
	v_add_f32_e32 v155, v209, v155
	v_add_f32_e32 v162, v210, v162
	v_add_f32_e32 v163, v211, v163
	v_add_f32_e32 v164, v212, v164
	v_add_f32_e32 v155, v213, v155
	v_add_f32_e32 v162, v214, v162
	v_add_f32_e32 v163, v215, v163
	v_add_f32_e32 v164, v216, v164
	v_add_f32_e32 v155, v155, v162
	v_add_f32_e32 v162, v163, v164
	v_add_f32_e32 v155, v155, v162
	v_fmamk_f32 v98, v98, 0x3e38aa3b, v150
	v_add_f32_e32 v153, v153, v155
	v_exp_f32_e32 v155, v98
	v_fmamk_f32 v98, v99, 0x3e38aa3b, v150
	v_fmamk_f32 v82, v82, 0x3e38aa3b, v150
	v_exp_f32_e32 v162, v98
	v_fmamk_f32 v98, v100, 0x3e38aa3b, v150
	v_exp_f32_e32 v201, v82
	v_fmamk_f32 v82, v83, 0x3e38aa3b, v150
	v_exp_f32_e32 v163, v98
	v_fmamk_f32 v98, v101, 0x3e38aa3b, v150
	v_exp_f32_e32 v202, v82
	v_fmamk_f32 v82, v84, 0x3e38aa3b, v150
	v_exp_f32_e32 v164, v98
	v_fmamk_f32 v98, v102, 0x3e38aa3b, v150
	v_exp_f32_e32 v203, v82
	v_fmamk_f32 v82, v85, 0x3e38aa3b, v150
	v_exp_f32_e32 v166, v98
	v_fmamk_f32 v98, v103, 0x3e38aa3b, v150
	v_exp_f32_e32 v204, v82
	v_fmamk_f32 v82, v86, 0x3e38aa3b, v150
	v_exp_f32_e32 v167, v98
	v_fmamk_f32 v98, v104, 0x3e38aa3b, v150
	v_exp_f32_e32 v205, v82
	v_fmamk_f32 v82, v87, 0x3e38aa3b, v150
	v_exp_f32_e32 v168, v98
	v_fmamk_f32 v98, v105, 0x3e38aa3b, v150
	v_exp_f32_e32 v206, v82
	v_fmamk_f32 v82, v88, 0x3e38aa3b, v150
	v_exp_f32_e32 v169, v98
	v_fmamk_f32 v98, v106, 0x3e38aa3b, v150
	v_exp_f32_e32 v207, v82
	v_fmamk_f32 v82, v89, 0x3e38aa3b, v150
	v_exp_f32_e32 v181, v98
	v_fmamk_f32 v98, v107, 0x3e38aa3b, v150
	v_exp_f32_e32 v208, v82
	v_fmamk_f32 v82, v90, 0x3e38aa3b, v150
	v_exp_f32_e32 v182, v98
	v_fmamk_f32 v98, v108, 0x3e38aa3b, v150
	v_exp_f32_e32 v209, v82
	v_fmamk_f32 v82, v91, 0x3e38aa3b, v150
	v_exp_f32_e32 v183, v98
	v_fmamk_f32 v98, v109, 0x3e38aa3b, v150
	v_exp_f32_e32 v210, v82
	v_fmamk_f32 v82, v92, 0x3e38aa3b, v150
	v_exp_f32_e32 v196, v98
	v_fmamk_f32 v98, v110, 0x3e38aa3b, v150
	v_exp_f32_e32 v211, v82
	v_fmamk_f32 v82, v93, 0x3e38aa3b, v150
	v_exp_f32_e32 v197, v98
	v_fmamk_f32 v98, v111, 0x3e38aa3b, v150
	v_exp_f32_e32 v212, v82
	v_fmamk_f32 v82, v94, 0x3e38aa3b, v150
	v_exp_f32_e32 v198, v98
	v_fmamk_f32 v98, v112, 0x3e38aa3b, v150
	v_exp_f32_e32 v213, v82
	v_fmamk_f32 v82, v95, 0x3e38aa3b, v150
	v_exp_f32_e32 v199, v98
	v_fmamk_f32 v98, v113, 0x3e38aa3b, v150
	v_exp_f32_e32 v214, v82
	v_fmamk_f32 v82, v96, 0x3e38aa3b, v150
	v_exp_f32_e32 v200, v98
	v_exp_f32_e32 v215, v82
	v_fmamk_f32 v82, v97, 0x3e38aa3b, v150
	ds_read_b64_tr_b16 v[94:95], v179 offset:30720
	ds_read_b64_tr_b16 v[96:97], v179 offset:32256
	ds_read_b64_tr_b16 v[100:101], v179 offset:32320
	ds_read_b64_tr_b16 v[98:99], v179 offset:30784
	v_exp_f32_e32 v216, v82
	v_cvt_pk_bf16_f32 v82, v155, v162
	v_cvt_pk_bf16_f32 v83, v163, v164
	v_cvt_pk_bf16_f32 v84, v166, v167
	v_cvt_pk_bf16_f32 v85, v168, v169
	v_cvt_pk_bf16_f32 v86, v181, v182
	v_cvt_pk_bf16_f32 v87, v183, v196
	v_cvt_pk_bf16_f32 v88, v197, v198
	v_cvt_pk_bf16_f32 v89, v199, v200
	v_cvt_pk_bf16_f32 v90, v201, v202
	v_cvt_pk_bf16_f32 v91, v203, v204
	v_cvt_pk_bf16_f32 v92, v205, v206
	v_cvt_pk_bf16_f32 v93, v207, v208
	v_cvt_pk_bf16_f32 v102, v209, v210
	v_cvt_pk_bf16_f32 v103, v211, v212
	v_cvt_pk_bf16_f32 v104, v213, v214
	v_cvt_pk_bf16_f32 v105, v215, v216
	s_waitcnt lgkmcnt(2)
	v_mfma_f32_32x32x16_bf16 v[66:81], v[94:97], v[82:85], v[66:81]
	ds_read_b64_tr_b16 v[94:95], v179 offset:33792
	ds_read_b64_tr_b16 v[96:97], v179 offset:35328
	ds_read_b64_tr_b16 v[108:109], v179 offset:35392
	ds_read_b64_tr_b16 v[106:107], v179 offset:33856
	s_waitcnt lgkmcnt(4)
	v_mfma_f32_32x32x16_bf16 v[34:49], v[98:101], v[82:85], v[34:49]
	s_waitcnt lgkmcnt(2)
	v_mfma_f32_32x32x16_bf16 v[66:81], v[94:97], v[86:89], v[66:81]
	ds_read_b64_tr_b16 v[82:83], v179 offset:36864
	ds_read_b64_tr_b16 v[84:85], v179 offset:38400
	ds_read_b64_tr_b16 v[96:97], v179 offset:38464
	ds_read_b64_tr_b16 v[94:95], v179 offset:36928
	s_waitcnt lgkmcnt(4)
	v_mfma_f32_32x32x16_bf16 v[34:49], v[106:109], v[86:89], v[34:49]
	s_waitcnt lgkmcnt(2)
	v_mfma_f32_32x32x16_bf16 v[66:81], v[82:85], v[90:93], v[66:81]
	ds_read_b64_tr_b16 v[82:83], v179 offset:39936
	ds_read_b64_tr_b16 v[84:85], v179 offset:41472
	ds_read_b64_tr_b16 v[88:89], v179 offset:41536
	ds_read_b64_tr_b16 v[86:87], v179 offset:40000
	s_waitcnt lgkmcnt(4)
	v_mfma_f32_32x32x16_bf16 v[34:49], v[94:97], v[90:93], v[34:49]
	s_waitcnt lgkmcnt(2)
	v_mfma_f32_32x32x16_bf16 v[66:81], v[82:85], v[102:105], v[66:81]
	s_waitcnt lgkmcnt(0)
	v_mfma_f32_32x32x16_bf16 v[34:49], v[86:89], v[102:105], v[34:49]
	s_mov_b32 s2, 0x168000
	v_add_co_u32_e32 v82, vcc, s2, v148
	s_waitcnt vmcnt(1)
	ds_write_b128 v174, v[134:137]
	s_waitcnt vmcnt(0)
	ds_write_b128 v165, v[138:141] offset:9216
	v_addc_co_u32_e32 v83, vcc, 0, v149, vcc
	s_waitcnt lgkmcnt(0)
	s_barrier
; #define LAS __attribute__((address_space(3)))
; #define SCHED_FENCE() __builtin_amdgcn_sched_barrier(0)
; template <int DQK, int KSB>
; __device__ __forceinline__ void attn_scores(LAS const unsigned char* Kt, const bf16x8 (&qf)[DQK / 16], f32x16 (&p)[2], int r32, int hi) {
;     constexpr int NK = DQK / 16;
;     LAS const unsigned char* kp = Kt + r32 * KSB + hi * 16;
;     f32x16 p0, p1;
; #pragma unroll
;     for (int e = 0; e < 16; ++e) { p0[e] = 0.f; p1[e] = 0.f; }
;     bf16x8 kr[3][2];
;     ...
;     QK_LOAD(0); QK_LOAD(1); SCHED_FENCE();
; #pragma unroll
;     for (int ks = 0; ks < NK; ++ks) {
;         if (ks + 2 < NK) QK_LOAD(ks + 2);
;         p0 = MFMA32(kr[ks % 3][0], qf[ks], p0); p1 = MFMA32(kr[ks % 3][1], qf[ks], p1); SCHED_FENCE();
;     }
;     ...
;     p[0] = p0; p[1] = p1;
; }
; template <int DV, bool MASK>
; __device__ __forceinline__ void attn_softmax(f32x16 (&p)[2], f32x16 (&o)[DV / 32], float& m, float& l, float cs, int hi, int dq) {
;     if (MASK) { if (__builtin_amdgcn_readfirstlane(dq) != NO_MASK) {
; #pragma unroll
;         for (int kvb = 0; kvb < 2; ++kvb)
; #pragma unroll
;             for (int e = 0; e < 16; ++e) { const int rel = dq + 32 * kvb + (e & 3) + 8 * (e >> 2) + 4 * hi; if (rel > 128 || rel < -128) p[kvb][e] = -INFINITY; } } }
;     float mx;
;     {
;         float a0 = fmaxf(fmaxf(p[0][0], p[0][1]), p[0][2]), a1 = fmaxf(fmaxf(p[0][8], p[0][9]), p[0][10]), a2 = fmaxf(fmaxf(p[1][0], p[1][1]), p[1][2]), a3 = fmaxf(fmaxf(p[1][8], p[1][9]), p[1][10]);
;         a0 = fmaxf(fmaxf(a0, p[0][3]), p[0][4]); a1 = fmaxf(fmaxf(a1, p[0][11]), p[0][12]); a2 = fmaxf(fmaxf(a2, p[1][3]), p[1][4]); a3 = fmaxf(fmaxf(a3, p[1][11]), p[1][12]);
; __device__ __forceinline__ void swa_unit(const bf16* Z, const float* sink  , bf16* Y, int b, int g, int blk, int cblk, LAS unsigned char* L, int tid) {
;     ...
;     for (int t = 0; t < ntiles; ++t) {
;         const bool more = t + 1 < ntiles;
;         if (more) SWA_LOAD(t + 1);
;         LAS const unsigned char* Kt = L + (t & 1) * SWA_BUF;
;         const int kpos0 = 64 * (wlo + t - 4);
;         const bool edge = t >= 4 && (wlo + t - 4 == blk - 2 || wlo + t - 4 == blk + 2);
; #pragma unroll
;         for (int sb = 0; sb < 2; ++sb) attn_tile<64, 64, SWA_KSB, SWA_VRB, true>(Kt, Kt + SWA_KT, qf[sb], o[sb], m[sb], l[sb], cs, r32, hi, vtb, edge ? kpos0 - (64 * blk + 32 * sb + r32) : NO_MASK);
	global_load_dwordx4 v[134:137], v[82:83], off
	global_load_dwordx4 v[138:141], v[82:83], off offset:256
	ds_read_b128 v[82:85], v145
	ds_read_b128 v[186:189], v145 offset:32
	ds_read_b128 v[86:89], v145 offset:4608
	ds_read_b128 v[218:221], v145 offset:4640
	s_waitcnt lgkmcnt(3)
	v_mfma_f32_32x32x16_bf16 v[98:113], v[82:85], v[130:133], 0
	ds_read_b128 v[222:225], v145 offset:64
	ds_read_b128 v[226:229], v145 offset:4672
	s_waitcnt lgkmcnt(3)
	v_mfma_f32_32x32x16_bf16 v[82:97], v[86:89], v[130:133], 0
	v_mfma_f32_32x32x16_bf16 v[98:113], v[186:189], v[126:129], v[98:113]
	ds_read_b128 v[186:189], v145 offset:96
	ds_read_b128 v[240:243], v145 offset:4704
	s_waitcnt lgkmcnt(4)
	v_mfma_f32_32x32x16_bf16 v[82:97], v[218:221], v[126:129], v[82:97]
	s_waitcnt lgkmcnt(3)
	v_mfma_f32_32x32x16_bf16 v[98:113], v[222:225], v[122:125], v[98:113]
	s_waitcnt lgkmcnt(2)
	v_mfma_f32_32x32x16_bf16 v[82:97], v[226:229], v[122:125], v[82:97]
	s_waitcnt lgkmcnt(1)
	v_mfma_f32_32x32x16_bf16 v[98:113], v[186:189], v[118:121], v[98:113]
	s_waitcnt lgkmcnt(0)
	v_mfma_f32_32x32x16_bf16 v[82:97], v[240:243], v[118:121], v[82:97]
	s_nop 10
	v_max_f32_e32 v148, v98, v99
	v_max_f32_e32 v187, v90, v91
	v_max_f32_e32 v149, v106, v107
	v_max3_f32 v186, v82, v83, v84
	v_max3_f32 v187, v187, v92, v93
	v_max3_f32 v148, v148, v100, v101
	v_max3_f32 v149, v149, v108, v109
	v_max3_f32 v186, v186, v85, v86
	v_max3_f32 v187, v187, v94, v95
	v_max3_f32 v148, v148, v102, v103
	v_max3_f32 v149, v149, v110, v111
	v_max3_f32 v186, v186, v87, v88
	v_max3_f32 v187, v187, v96, v97
	v_max3_f32 v148, v148, v104, v105
	v_max3_f32 v149, v149, v112, v113
	v_max3_f32 v186, v186, v89, v187
	v_max3_f32 v148, v148, v149, v186
	v_mov_b32_e32 v149, v148
	s_nop 1
	v_permlane32_swap_b32_e32 v148, v149
	v_max_f32_e32 v148, v148, v149
	v_mul_f32_e32 v148, 0x3e38aa3b, v148
	s_nop 0
	v_max_f32_e32 v148, v152, v148
	v_sub_f32_e32 v149, v148, v152
	v_cmp_lt_f32_e32 vcc, s34, v149
	s_cbranch_vccz .LBB0_841
	v_sub_f32_e32 v147, v152, v148
	v_exp_f32_e32 v152, v147
	v_xor_b32_e32 v147, 0x80000000, v148
	v_mul_f32_e32 v153, v153, v152
	v_pk_mul_f32 v[64:65], v[64:65], v[152:153] op_sel_hi:[1,0]
	v_pk_mul_f32 v[62:63], v[62:63], v[152:153] op_sel_hi:[1,0]
	v_pk_mul_f32 v[60:61], v[60:61], v[152:153] op_sel_hi:[1,0]
	v_pk_mul_f32 v[58:59], v[58:59], v[152:153] op_sel_hi:[1,0]
	v_pk_mul_f32 v[56:57], v[56:57], v[152:153] op_sel_hi:[1,0]
	v_pk_mul_f32 v[54:55], v[54:55], v[152:153] op_sel_hi:[1,0]
	v_pk_mul_f32 v[52:53], v[52:53], v[152:153] op_sel_hi:[1,0]
	v_pk_mul_f32 v[50:51], v[50:51], v[152:153] op_sel_hi:[1,0]
	v_pk_mul_f32 v[16:17], v[16:17], v[152:153] op_sel_hi:[1,0]
	v_pk_mul_f32 v[14:15], v[14:15], v[152:153] op_sel_hi:[1,0]
	v_pk_mul_f32 v[12:13], v[12:13], v[152:153] op_sel_hi:[1,0]
	v_pk_mul_f32 v[10:11], v[10:11], v[152:153] op_sel_hi:[1,0]
	v_pk_mul_f32 v[8:9], v[8:9], v[152:153] op_sel_hi:[1,0]
	v_pk_mul_f32 v[6:7], v[6:7], v[152:153] op_sel_hi:[1,0]
	v_pk_mul_f32 v[4:5], v[4:5], v[152:153] op_sel_hi:[1,0]
	v_pk_mul_f32 v[2:3], v[2:3], v[152:153] op_sel_hi:[1,0]
	s_branch .LBB0_842

; #define LAS __attribute__((address_space(3)))
; __device__ __forceinline__ unsigned pk2(float lo, float hi) { return pg8::pkbf(lo, hi); }
; __device__ __forceinline__ float fexp2(float x) { return __builtin_amdgcn_exp2f(x); }
; #define SCHED_FENCE() __builtin_amdgcn_sched_barrier(0)
; #define PV_LOAD(dst, i) do { _Pragma("unroll") for (int d = 0; d < ND; ++d) { LAS const unsigned char* vp = vb + (16 * (i)) * VRB + d * 64; dst[2 * d] = tr_read(vp); dst[2 * d + 1] = tr_read(vp + 8 * VRB); } } while (0)
; #define PV_MMA(src, i) do { _Pragma("unroll") for (int d = 0; d < ND; ++d) { const bf16x8 vf = __builtin_shufflevector(src[2 * d], src[2 * d + 1], 0, 1, 2, 3, 4, 5, 6, 7); o[d] = MFMA32(vf, pf[i], o[d]); } } while (0)
; template <int DV, bool MASK>
; __device__ __forceinline__ void attn_softmax(f32x16 (&p)[2], f32x16 (&o)[DV / 32], float& m, float& l, float cs, int hi, int dq) {
;     ...
;     float ls0 = 0.f, ls1 = 0.f, ls2 = 0.f, ls3 = 0.f;
; #pragma unroll
;     for (int kvb = 0; kvb < 2; ++kvb)
; #pragma unroll
;         for (int e = 0; e < 16; e += 4) {
;             const float e0 = fexp2(fmaf(p[kvb][e], cs, -m)), e1 = fexp2(fmaf(p[kvb][e + 1], cs, -m)), e2 = fexp2(fmaf(p[kvb][e + 2], cs, -m)), e3 = fexp2(fmaf(p[kvb][e + 3], cs, -m));
;             p[kvb][e] = e0; p[kvb][e + 1] = e1; p[kvb][e + 2] = e2; p[kvb][e + 3] = e3; ls0 += e0; ls1 += e1; ls2 += e2; ls3 += e3; }
;     l += (ls0 + ls1) + (ls2 + ls3);
; }
; template <int DV, int VRB>
; __device__ __forceinline__ void attn_pv(LAS const unsigned char* Vt, const f32x16 (&p)[2], f32x16 (&o)[DV / 32], int vtb) {
;     constexpr int ND = DV / 32;
;     LAS const unsigned char* vb = Vt + vtb;
;     bf16x8 pf[4];
; #pragma unroll
;     for (int i = 0; i < 4; ++i) { const int kvb = i >> 1, s = i & 1;
;         v4u pw; pw.x = pk2(p[kvb][8 * s + 0], p[kvb][8 * s + 1]); pw.y = pk2(p[kvb][8 * s + 2], p[kvb][8 * s + 3]); pw.z = pk2(p[kvb][8 * s + 4], p[kvb][8 * s + 5]); pw.w = pk2(p[kvb][8 * s + 6], p[kvb][8 * s + 7]);
;         pf[i] = __builtin_bit_cast(bf16x8, pw); }
;     s16x4 va[2 * ND], vbq[2 * ND];
;     ...
;     PV_LOAD(va, 0); SCHED_FENCE();
;     PV_LOAD(vbq, 1); PV_MMA(va, 0); SCHED_FENCE();
;     PV_LOAD(va, 2); PV_MMA(vbq, 1); SCHED_FENCE();
;     PV_LOAD(vbq, 3); PV_MMA(va, 2); SCHED_FENCE();
.LBB0_842:
	v_add_f32_e32 v149, 0, v155
	v_add_f32_e32 v152, 0, v162
	v_add_f32_e32 v155, 0, v163
	v_add_f32_e32 v162, 0, v164
	v_add_f32_e32 v149, v166, v149
	v_add_f32_e32 v152, v167, v152
	v_add_f32_e32 v155, v168, v155
	v_add_f32_e32 v162, v169, v162
	v_add_f32_e32 v149, v181, v149
	v_add_f32_e32 v152, v182, v152
	v_add_f32_e32 v155, v183, v155
	v_add_f32_e32 v162, v196, v162
	v_add_f32_e32 v149, v197, v149
	v_add_f32_e32 v152, v198, v152
	v_add_f32_e32 v155, v199, v155
	v_add_f32_e32 v162, v200, v162
	v_add_f32_e32 v149, v201, v149
	v_add_f32_e32 v152, v202, v152
	v_add_f32_e32 v155, v203, v155
	v_add_f32_e32 v162, v204, v162
	v_add_f32_e32 v149, v205, v149
	v_add_f32_e32 v152, v206, v152
	v_add_f32_e32 v155, v207, v155
	v_add_f32_e32 v162, v208, v162
	v_add_f32_e32 v149, v209, v149
	v_add_f32_e32 v152, v210, v152
	v_add_f32_e32 v155, v211, v155
	v_add_f32_e32 v162, v212, v162
	v_add_f32_e32 v149, v213, v149
	v_add_f32_e32 v152, v214, v152
	v_add_f32_e32 v155, v215, v155
	v_add_f32_e32 v162, v216, v162
	v_add_f32_e32 v149, v149, v152
	v_add_f32_e32 v152, v155, v162
	v_add_f32_e32 v149, v149, v152
	v_fmamk_f32 v98, v98, 0x3e38aa3b, v147
	v_add_f32_e32 v152, v154, v149
	v_exp_f32_e32 v154, v98
	v_fmamk_f32 v98, v99, 0x3e38aa3b, v147
	v_fmamk_f32 v82, v82, 0x3e38aa3b, v147
	v_exp_f32_e32 v155, v98
	v_fmamk_f32 v98, v100, 0x3e38aa3b, v147
	v_exp_f32_e32 v200, v82
	v_fmamk_f32 v82, v83, 0x3e38aa3b, v147
	v_exp_f32_e32 v162, v98
	v_fmamk_f32 v98, v101, 0x3e38aa3b, v147
	v_exp_f32_e32 v201, v82
	v_fmamk_f32 v82, v84, 0x3e38aa3b, v147
	v_exp_f32_e32 v163, v98
	v_fmamk_f32 v98, v102, 0x3e38aa3b, v147
	v_exp_f32_e32 v202, v82
	v_fmamk_f32 v82, v85, 0x3e38aa3b, v147
	v_exp_f32_e32 v164, v98
	v_fmamk_f32 v98, v103, 0x3e38aa3b, v147
	v_exp_f32_e32 v203, v82
	v_fmamk_f32 v82, v86, 0x3e38aa3b, v147
	v_exp_f32_e32 v166, v98
	v_fmamk_f32 v98, v104, 0x3e38aa3b, v147
	v_exp_f32_e32 v204, v82
	v_fmamk_f32 v82, v87, 0x3e38aa3b, v147
	v_exp_f32_e32 v167, v98
	v_fmamk_f32 v98, v105, 0x3e38aa3b, v147
	v_exp_f32_e32 v205, v82
	v_fmamk_f32 v82, v88, 0x3e38aa3b, v147
	v_exp_f32_e32 v168, v98
	v_fmamk_f32 v98, v106, 0x3e38aa3b, v147
	v_exp_f32_e32 v206, v82
	v_fmamk_f32 v82, v89, 0x3e38aa3b, v147
	v_exp_f32_e32 v169, v98
	v_fmamk_f32 v98, v107, 0x3e38aa3b, v147
	v_exp_f32_e32 v207, v82
	v_fmamk_f32 v82, v90, 0x3e38aa3b, v147
	v_exp_f32_e32 v181, v98
	v_fmamk_f32 v98, v108, 0x3e38aa3b, v147
	v_exp_f32_e32 v208, v82
	v_fmamk_f32 v82, v91, 0x3e38aa3b, v147
	v_exp_f32_e32 v182, v98
	v_fmamk_f32 v98, v109, 0x3e38aa3b, v147
	v_exp_f32_e32 v209, v82
	v_fmamk_f32 v82, v92, 0x3e38aa3b, v147
	v_exp_f32_e32 v183, v98
	v_fmamk_f32 v98, v110, 0x3e38aa3b, v147
	v_exp_f32_e32 v210, v82
	v_fmamk_f32 v82, v93, 0x3e38aa3b, v147
	v_exp_f32_e32 v196, v98
	v_fmamk_f32 v98, v111, 0x3e38aa3b, v147
	v_exp_f32_e32 v211, v82
	v_fmamk_f32 v82, v94, 0x3e38aa3b, v147
	v_exp_f32_e32 v197, v98
	v_fmamk_f32 v98, v112, 0x3e38aa3b, v147
	v_exp_f32_e32 v212, v82
	v_fmamk_f32 v82, v95, 0x3e38aa3b, v147
	v_exp_f32_e32 v198, v98
	v_fmamk_f32 v98, v113, 0x3e38aa3b, v147
	v_exp_f32_e32 v213, v82
	v_fmamk_f32 v82, v96, 0x3e38aa3b, v147
	v_exp_f32_e32 v199, v98
	v_exp_f32_e32 v214, v82
	v_fmamk_f32 v82, v97, 0x3e38aa3b, v147
	ds_read_b64_tr_b16 v[94:95], v179 offset:9216
	ds_read_b64_tr_b16 v[96:97], v179 offset:10752
	ds_read_b64_tr_b16 v[100:101], v179 offset:10816
	ds_read_b64_tr_b16 v[98:99], v179 offset:9280
	v_exp_f32_e32 v215, v82
	v_cvt_pk_bf16_f32 v82, v154, v155
	v_cvt_pk_bf16_f32 v83, v162, v163
	v_cvt_pk_bf16_f32 v84, v164, v166
	v_cvt_pk_bf16_f32 v85, v167, v168
	v_cvt_pk_bf16_f32 v86, v169, v181
	v_cvt_pk_bf16_f32 v87, v182, v183
	v_cvt_pk_bf16_f32 v88, v196, v197
	v_cvt_pk_bf16_f32 v89, v198, v199
	v_cvt_pk_bf16_f32 v90, v200, v201
	v_cvt_pk_bf16_f32 v91, v202, v203
	v_cvt_pk_bf16_f32 v92, v204, v205
	v_cvt_pk_bf16_f32 v93, v206, v207
	v_cvt_pk_bf16_f32 v102, v208, v209
	v_cvt_pk_bf16_f32 v103, v210, v211
	v_cvt_pk_bf16_f32 v104, v212, v213
	v_cvt_pk_bf16_f32 v105, v214, v215
	s_waitcnt lgkmcnt(2)
; #define LAS __attribute__((address_space(3)))
; template <int DQK, int KSB>
; __device__ __forceinline__ void attn_scores(LAS const unsigned char* Kt, const bf16x8 (&qf)[DQK / 16], f32x16 (&p)[2], int r32, int hi) {
;     constexpr int NK = DQK / 16;
;     LAS const unsigned char* kp = Kt + r32 * KSB + hi * 16;
;     f32x16 p0, p1;
; #pragma unroll
;     for (int e = 0; e < 16; ++e) { p0[e] = 0.f; p1[e] = 0.f; }
;     bf16x8 kr[3][2];
;     ...
;     QK_LOAD(0); QK_LOAD(1); SCHED_FENCE();
; #pragma unroll
;     for (int ks = 0; ks < NK; ++ks) {
;         if (ks + 2 < NK) QK_LOAD(ks + 2);
;         p0 = MFMA32(kr[ks % 3][0], qf[ks], p0); p1 = MFMA32(kr[ks % 3][1], qf[ks], p1); SCHED_FENCE();
;     }
;     ...
;     p[0] = p0; p[1] = p1;
; }
; template <int DV, bool MASK>
; __device__ __forceinline__ void attn_softmax(f32x16 (&p)[2], f32x16 (&o)[DV / 32], float& m, float& l, float cs, int hi, int dq) {
;     if (MASK) { if (__builtin_amdgcn_readfirstlane(dq) != NO_MASK) {
; #pragma unroll
;         for (int kvb = 0; kvb < 2; ++kvb)
; #pragma unroll
;             for (int e = 0; e < 16; ++e) { const int rel = dq + 32 * kvb + (e & 3) + 8 * (e >> 2) + 4 * hi; if (rel > 128 || rel < -128) p[kvb][e] = -INFINITY; } } }
;     float mx;
;     {
;         float a0 = fmaxf(fmaxf(p[0][0], p[0][1]), p[0][2]), a1 = fmaxf(fmaxf(p[0][8], p[0][9]), p[0][10]), a2 = fmaxf(fmaxf(p[1][0], p[1][1]), p[1][2]), a3 = fmaxf(fmaxf(p[1][8], p[1][9]), p[1][10]);
;         a0 = fmaxf(fmaxf(a0, p[0][3]), p[0][4]); a1 = fmaxf(fmaxf(a1, p[0][11]), p[0][12]); a2 = fmaxf(fmaxf(a2, p[1][3]), p[1][4]); a3 = fmaxf(fmaxf(a3, p[1][11]), p[1][12]);
;         a0 = fmaxf(fmaxf(a0, p[0][5]), p[0][6]); a1 = fmaxf(fmaxf(a1, p[0][13]), p[0][14]); a2 = fmaxf(fmaxf(a2, p[1][5]), p[1][6]); a3 = fmaxf(fmaxf(a3, p[1][13]), p[1][14]);
;         a0 = fmaxf(a0, p[0][7]); a1 = fmaxf(a1, p[0][15]); a2 = fmaxf(a2, p[1][7]); a3 = fmaxf(a3, p[1][15]);
;         mx = fmaxf(fmaxf(a0, a1), fmaxf(a2, a3));
; template <int DV, int VRB>
; __device__ __forceinline__ void attn_pv(LAS const unsigned char* Vt, const f32x16 (&p)[2], f32x16 (&o)[DV / 32], int vtb) {
;     ...
;     PV_LOAD(va, 0); SCHED_FENCE();
;     PV_LOAD(vbq, 1); PV_MMA(va, 0); SCHED_FENCE();
;     PV_LOAD(va, 2); PV_MMA(vbq, 1); SCHED_FENCE();
;     PV_LOAD(vbq, 3); PV_MMA(va, 2); SCHED_FENCE();
;     PV_MMA(vbq, 3); SCHED_FENCE();
	v_mfma_f32_32x32x16_bf16 v[50:65], v[94:97], v[82:85], v[50:65]
	ds_read_b64_tr_b16 v[94:95], v179 offset:12288
	ds_read_b64_tr_b16 v[96:97], v179 offset:13824
	ds_read_b64_tr_b16 v[108:109], v179 offset:13888
	ds_read_b64_tr_b16 v[106:107], v179 offset:12352
	s_waitcnt lgkmcnt(4)
	v_mfma_f32_32x32x16_bf16 v[2:17], v[98:101], v[82:85], v[2:17]
	s_waitcnt lgkmcnt(2)
	v_mfma_f32_32x32x16_bf16 v[50:65], v[94:97], v[86:89], v[50:65]
	ds_read_b64_tr_b16 v[82:83], v179 offset:15360
	ds_read_b64_tr_b16 v[84:85], v179 offset:16896
	ds_read_b64_tr_b16 v[96:97], v179 offset:16960
	ds_read_b64_tr_b16 v[94:95], v179 offset:15424
	s_waitcnt lgkmcnt(4)
	v_mfma_f32_32x32x16_bf16 v[2:17], v[106:109], v[86:89], v[2:17]
	s_waitcnt lgkmcnt(2)
	v_mfma_f32_32x32x16_bf16 v[50:65], v[82:85], v[90:93], v[50:65]
	ds_read_b64_tr_b16 v[82:83], v179 offset:18432
	ds_read_b64_tr_b16 v[84:85], v179 offset:19968
	ds_read_b64_tr_b16 v[88:89], v179 offset:20032
	ds_read_b64_tr_b16 v[86:87], v179 offset:18496
	s_waitcnt lgkmcnt(4)
	v_mfma_f32_32x32x16_bf16 v[2:17], v[94:97], v[90:93], v[2:17]
	s_waitcnt lgkmcnt(2)
	v_mfma_f32_32x32x16_bf16 v[50:65], v[82:85], v[102:105], v[50:65]
	s_waitcnt lgkmcnt(0)
	v_mfma_f32_32x32x16_bf16 v[2:17], v[86:89], v[102:105], v[2:17]
	ds_read_b128 v[82:85], v145
	ds_read_b128 v[186:189], v145 offset:32
	ds_read_b128 v[86:89], v145 offset:4608
	ds_read_b128 v[216:219], v145 offset:4640
	s_waitcnt lgkmcnt(3)
	v_mfma_f32_32x32x16_bf16 v[98:113], v[82:85], v[114:117], 0
	ds_read_b128 v[220:223], v145 offset:64
	ds_read_b128 v[224:227], v145 offset:4672
	s_waitcnt lgkmcnt(3)
	v_mfma_f32_32x32x16_bf16 v[82:97], v[86:89], v[114:117], 0
	v_mfma_f32_32x32x16_bf16 v[98:113], v[186:189], v[26:29], v[98:113]
	ds_read_b128 v[186:189], v145 offset:96
	ds_read_b128 v[240:243], v145 offset:4704
	s_waitcnt lgkmcnt(4)
	v_mfma_f32_32x32x16_bf16 v[82:97], v[216:219], v[26:29], v[82:97]
	s_waitcnt lgkmcnt(3)
	v_mfma_f32_32x32x16_bf16 v[98:113], v[220:223], v[22:25], v[98:113]
	s_waitcnt lgkmcnt(2)
	v_mfma_f32_32x32x16_bf16 v[82:97], v[224:227], v[22:25], v[82:97]
	s_waitcnt lgkmcnt(1)
	v_mfma_f32_32x32x16_bf16 v[98:113], v[186:189], v[18:21], v[98:113]
	s_waitcnt lgkmcnt(0)
	v_mfma_f32_32x32x16_bf16 v[82:97], v[240:243], v[18:21], v[82:97]
	s_nop 10
	v_max_f32_e32 v149, v98, v99
	v_max_f32_e32 v188, v90, v91
	v_max_f32_e32 v186, v106, v107
	v_max3_f32 v187, v82, v83, v84
	v_max3_f32 v188, v188, v92, v93
	v_max3_f32 v149, v149, v100, v101
	v_max3_f32 v186, v186, v108, v109
	v_max3_f32 v187, v187, v85, v86
	v_max3_f32 v188, v188, v94, v95
	v_max3_f32 v149, v149, v102, v103
	v_max3_f32 v186, v186, v110, v111
	v_max3_f32 v187, v187, v87, v88
	v_max3_f32 v188, v188, v96, v97
	v_max3_f32 v149, v149, v104, v105
	v_max3_f32 v186, v186, v112, v113
	v_max3_f32 v187, v187, v89, v188
	v_max3_f32 v149, v149, v186, v187
	v_mov_b32_e32 v186, v149
	s_nop 1
	v_permlane32_swap_b32_e32 v149, v186
	v_max_f32_e32 v149, v149, v186
	v_mul_f32_e32 v149, 0x3e38aa3b, v149
	s_nop 0
	v_max_f32_e32 v149, v151, v149
	v_sub_f32_e32 v186, v149, v151
	v_cmp_lt_f32_e32 vcc, s34, v186
	s_cbranch_vccz .LBB0_844
	v_sub_f32_e32 v150, v151, v149
	v_exp_f32_e32 v150, v150
	s_nop 0
	v_mul_f32_e32 v152, v152, v150
	v_pk_mul_f32 v[80:81], v[80:81], v[150:151] op_sel_hi:[1,0]
	v_pk_mul_f32 v[78:79], v[78:79], v[150:151] op_sel_hi:[1,0]
	v_pk_mul_f32 v[76:77], v[76:77], v[150:151] op_sel_hi:[1,0]
	v_pk_mul_f32 v[74:75], v[74:75], v[150:151] op_sel_hi:[1,0]
	v_pk_mul_f32 v[72:73], v[72:73], v[150:151] op_sel_hi:[1,0]
	v_pk_mul_f32 v[70:71], v[70:71], v[150:151] op_sel_hi:[1,0]
	v_pk_mul_f32 v[68:69], v[68:69], v[150:151] op_sel_hi:[1,0]
	v_pk_mul_f32 v[66:67], v[66:67], v[150:151] op_sel_hi:[1,0]
	v_pk_mul_f32 v[48:49], v[48:49], v[150:151] op_sel_hi:[1,0]
	v_pk_mul_f32 v[46:47], v[46:47], v[150:151] op_sel_hi:[1,0]
	v_pk_mul_f32 v[44:45], v[44:45], v[150:151] op_sel_hi:[1,0]
	v_pk_mul_f32 v[42:43], v[42:43], v[150:151] op_sel_hi:[1,0]
	v_pk_mul_f32 v[40:41], v[40:41], v[150:151] op_sel_hi:[1,0]
	v_pk_mul_f32 v[38:39], v[38:39], v[150:151] op_sel_hi:[1,0]
	v_pk_mul_f32 v[36:37], v[36:37], v[150:151] op_sel_hi:[1,0]
	v_pk_mul_f32 v[34:35], v[34:35], v[150:151] op_sel_hi:[1,0]
	v_xor_b32_e32 v150, 0x80000000, v149
	s_branch .LBB0_845

; #define LAS __attribute__((address_space(3)))
; __device__ __forceinline__ unsigned pk2(float lo, float hi) { return pg8::pkbf(lo, hi); }
; __device__ __forceinline__ float fexp2(float x) { return __builtin_amdgcn_exp2f(x); }
; #define SCHED_FENCE() __builtin_amdgcn_sched_barrier(0)
; #define PV_LOAD(dst, i) do { _Pragma("unroll") for (int d = 0; d < ND; ++d) { LAS const unsigned char* vp = vb + (16 * (i)) * VRB + d * 64; dst[2 * d] = tr_read(vp); dst[2 * d + 1] = tr_read(vp + 8 * VRB); } } while (0)
; template <int DV, bool MASK>
; __device__ __forceinline__ void attn_softmax(f32x16 (&p)[2], f32x16 (&o)[DV / 32], float& m, float& l, float cs, int hi, int dq) {
;     ...
;     float ls0 = 0.f, ls1 = 0.f, ls2 = 0.f, ls3 = 0.f;
; #pragma unroll
;     for (int kvb = 0; kvb < 2; ++kvb)
; #pragma unroll
;         for (int e = 0; e < 16; e += 4) {
;             const float e0 = fexp2(fmaf(p[kvb][e], cs, -m)), e1 = fexp2(fmaf(p[kvb][e + 1], cs, -m)), e2 = fexp2(fmaf(p[kvb][e + 2], cs, -m)), e3 = fexp2(fmaf(p[kvb][e + 3], cs, -m));
;             p[kvb][e] = e0; p[kvb][e + 1] = e1; p[kvb][e + 2] = e2; p[kvb][e + 3] = e3; ls0 += e0; ls1 += e1; ls2 += e2; ls3 += e3; }
;     l += (ls0 + ls1) + (ls2 + ls3);
; }
; template <int DV, int VRB>
; __device__ __forceinline__ void attn_pv(LAS const unsigned char* Vt, const f32x16 (&p)[2], f32x16 (&o)[DV / 32], int vtb) {
;     constexpr int ND = DV / 32;
;     LAS const unsigned char* vb = Vt + vtb;
;     bf16x8 pf[4];
; #pragma unroll
;     for (int i = 0; i < 4; ++i) { const int kvb = i >> 1, s = i & 1;
;         v4u pw; pw.x = pk2(p[kvb][8 * s + 0], p[kvb][8 * s + 1]); pw.y = pk2(p[kvb][8 * s + 2], p[kvb][8 * s + 3]); pw.z = pk2(p[kvb][8 * s + 4], p[kvb][8 * s + 5]); pw.w = pk2(p[kvb][8 * s + 6], p[kvb][8 * s + 7]);
;         pf[i] = __builtin_bit_cast(bf16x8, pw); }
;     s16x4 va[2 * ND], vbq[2 * ND];
;     ...
;     PV_LOAD(va, 0); SCHED_FENCE();
;     PV_LOAD(vbq, 1); PV_MMA(va, 0); SCHED_FENCE();
;     PV_LOAD(va, 2); PV_MMA(vbq, 1); SCHED_FENCE();
;     PV_LOAD(vbq, 3); PV_MMA(va, 2); SCHED_FENCE();
;     PV_MMA(vbq, 3); SCHED_FENCE();
; __device__ __forceinline__ void swa_unit(const bf16* Z, const float* sink  , bf16* Y, int b, int g, int blk, int cblk, LAS unsigned char* L, int tid) {
;     ...
;         if (more) SWA_STORE((t + 1) & 1);
;         __syncthreads();
.LBB0_845:
	v_add_f32_e32 v151, 0, v154
	v_add_f32_e32 v154, 0, v155
	v_add_f32_e32 v155, 0, v162
	v_add_f32_e32 v162, 0, v163
	v_add_f32_e32 v151, v164, v151
	v_add_f32_e32 v154, v166, v154
	v_add_f32_e32 v155, v167, v155
	v_add_f32_e32 v162, v168, v162
	v_add_f32_e32 v151, v169, v151
	v_add_f32_e32 v154, v181, v154
	v_add_f32_e32 v155, v182, v155
	v_add_f32_e32 v162, v183, v162
	v_add_f32_e32 v151, v196, v151
	v_add_f32_e32 v154, v197, v154
	v_add_f32_e32 v155, v198, v155
	v_add_f32_e32 v162, v199, v162
	v_add_f32_e32 v151, v200, v151
	v_add_f32_e32 v154, v201, v154
	v_add_f32_e32 v155, v202, v155
	v_add_f32_e32 v162, v203, v162
	v_add_f32_e32 v151, v204, v151
	v_add_f32_e32 v154, v205, v154
	v_add_f32_e32 v155, v206, v155
	v_add_f32_e32 v162, v207, v162
	v_add_f32_e32 v151, v208, v151
	v_add_f32_e32 v154, v209, v154
	v_add_f32_e32 v155, v210, v155
	v_add_f32_e32 v162, v211, v162
	v_add_f32_e32 v151, v212, v151
	v_add_f32_e32 v154, v213, v154
	v_add_f32_e32 v155, v214, v155
	v_add_f32_e32 v162, v215, v162
	v_add_f32_e32 v151, v151, v154
	v_add_f32_e32 v154, v155, v162
	v_add_f32_e32 v151, v151, v154
	v_fmamk_f32 v98, v98, 0x3e38aa3b, v150
	v_add_f32_e32 v151, v153, v151
	v_exp_f32_e32 v153, v98
	v_fmamk_f32 v98, v99, 0x3e38aa3b, v150
	v_fmamk_f32 v82, v82, 0x3e38aa3b, v150
	v_exp_f32_e32 v154, v98
	v_fmamk_f32 v98, v100, 0x3e38aa3b, v150
	v_exp_f32_e32 v199, v82
	v_fmamk_f32 v82, v83, 0x3e38aa3b, v150
	v_exp_f32_e32 v155, v98
	v_fmamk_f32 v98, v101, 0x3e38aa3b, v150
	v_exp_f32_e32 v200, v82
	v_fmamk_f32 v82, v84, 0x3e38aa3b, v150
	v_exp_f32_e32 v162, v98
	v_fmamk_f32 v98, v102, 0x3e38aa3b, v150
	v_exp_f32_e32 v201, v82
	v_fmamk_f32 v82, v85, 0x3e38aa3b, v150
	v_exp_f32_e32 v163, v98
	v_fmamk_f32 v98, v103, 0x3e38aa3b, v150
	v_exp_f32_e32 v202, v82
	v_fmamk_f32 v82, v86, 0x3e38aa3b, v150
	v_exp_f32_e32 v164, v98
	v_fmamk_f32 v98, v104, 0x3e38aa3b, v150
	v_exp_f32_e32 v203, v82
	v_fmamk_f32 v82, v87, 0x3e38aa3b, v150
	v_exp_f32_e32 v166, v98
	v_fmamk_f32 v98, v105, 0x3e38aa3b, v150
	v_exp_f32_e32 v204, v82
	v_fmamk_f32 v82, v88, 0x3e38aa3b, v150
	v_exp_f32_e32 v167, v98
	v_fmamk_f32 v98, v106, 0x3e38aa3b, v150
	v_exp_f32_e32 v205, v82
	v_fmamk_f32 v82, v89, 0x3e38aa3b, v150
	v_exp_f32_e32 v168, v98
	v_fmamk_f32 v98, v107, 0x3e38aa3b, v150
	v_exp_f32_e32 v206, v82
	v_fmamk_f32 v82, v90, 0x3e38aa3b, v150
	v_exp_f32_e32 v169, v98
	v_fmamk_f32 v98, v108, 0x3e38aa3b, v150
	v_exp_f32_e32 v207, v82
	v_fmamk_f32 v82, v91, 0x3e38aa3b, v150
	v_exp_f32_e32 v181, v98
	v_fmamk_f32 v98, v109, 0x3e38aa3b, v150
	v_exp_f32_e32 v208, v82
	v_fmamk_f32 v82, v92, 0x3e38aa3b, v150
	v_exp_f32_e32 v182, v98
	v_fmamk_f32 v98, v110, 0x3e38aa3b, v150
	v_exp_f32_e32 v209, v82
	v_fmamk_f32 v82, v93, 0x3e38aa3b, v150
	v_exp_f32_e32 v183, v98
	v_fmamk_f32 v98, v111, 0x3e38aa3b, v150
	v_exp_f32_e32 v210, v82
	v_fmamk_f32 v82, v94, 0x3e38aa3b, v150
	v_exp_f32_e32 v196, v98
	v_fmamk_f32 v98, v112, 0x3e38aa3b, v150
	v_exp_f32_e32 v211, v82
	v_fmamk_f32 v82, v95, 0x3e38aa3b, v150
	v_exp_f32_e32 v197, v98
	v_fmamk_f32 v98, v113, 0x3e38aa3b, v150
	v_exp_f32_e32 v212, v82
	v_fmamk_f32 v82, v96, 0x3e38aa3b, v150
	v_exp_f32_e32 v198, v98
	v_exp_f32_e32 v213, v82
	v_fmamk_f32 v82, v97, 0x3e38aa3b, v150
	ds_read_b64_tr_b16 v[94:95], v179 offset:9216
	ds_read_b64_tr_b16 v[96:97], v179 offset:10752
	ds_read_b64_tr_b16 v[100:101], v179 offset:10816
	ds_read_b64_tr_b16 v[98:99], v179 offset:9280
	v_exp_f32_e32 v214, v82
	v_cvt_pk_bf16_f32 v82, v153, v154
	v_cvt_pk_bf16_f32 v83, v155, v162
	v_cvt_pk_bf16_f32 v84, v163, v164
	v_cvt_pk_bf16_f32 v85, v166, v167
	v_cvt_pk_bf16_f32 v86, v168, v169
	v_cvt_pk_bf16_f32 v87, v181, v182
	v_cvt_pk_bf16_f32 v88, v183, v196
	v_cvt_pk_bf16_f32 v89, v197, v198
	v_cvt_pk_bf16_f32 v90, v199, v200
	v_cvt_pk_bf16_f32 v91, v201, v202
	v_cvt_pk_bf16_f32 v92, v203, v204
	v_cvt_pk_bf16_f32 v93, v205, v206
	v_cvt_pk_bf16_f32 v102, v207, v208
	v_cvt_pk_bf16_f32 v103, v209, v210
	v_cvt_pk_bf16_f32 v104, v211, v212
	v_cvt_pk_bf16_f32 v105, v213, v214
	s_waitcnt lgkmcnt(2)
	v_mfma_f32_32x32x16_bf16 v[66:81], v[94:97], v[82:85], v[66:81]
	ds_read_b64_tr_b16 v[94:95], v179 offset:12288
	ds_read_b64_tr_b16 v[96:97], v179 offset:13824
	ds_read_b64_tr_b16 v[108:109], v179 offset:13888
	ds_read_b64_tr_b16 v[106:107], v179 offset:12352
	s_waitcnt lgkmcnt(4)
	v_mfma_f32_32x32x16_bf16 v[34:49], v[98:101], v[82:85], v[34:49]
	s_waitcnt lgkmcnt(2)
	v_mfma_f32_32x32x16_bf16 v[66:81], v[94:97], v[86:89], v[66:81]
	ds_read_b64_tr_b16 v[82:83], v179 offset:15360
	ds_read_b64_tr_b16 v[84:85], v179 offset:16896
	ds_read_b64_tr_b16 v[96:97], v179 offset:16960
	ds_read_b64_tr_b16 v[94:95], v179 offset:15424
	s_waitcnt lgkmcnt(4)
	v_mfma_f32_32x32x16_bf16 v[34:49], v[106:109], v[86:89], v[34:49]
	s_waitcnt lgkmcnt(2)
	v_mfma_f32_32x32x16_bf16 v[66:81], v[82:85], v[90:93], v[66:81]
	ds_read_b64_tr_b16 v[82:83], v179 offset:18432
	ds_read_b64_tr_b16 v[84:85], v179 offset:19968
	ds_read_b64_tr_b16 v[88:89], v179 offset:20032
	ds_read_b64_tr_b16 v[86:87], v179 offset:18496
	s_waitcnt lgkmcnt(4)
	v_mfma_f32_32x32x16_bf16 v[34:49], v[94:97], v[90:93], v[34:49]
	s_waitcnt lgkmcnt(2)
	v_mfma_f32_32x32x16_bf16 v[66:81], v[82:85], v[102:105], v[66:81]
	s_waitcnt lgkmcnt(0)
	v_mfma_f32_32x32x16_bf16 v[34:49], v[86:89], v[102:105], v[34:49]
	s_waitcnt vmcnt(1)
	ds_write_b128 v174, v[134:137] offset:21504
	s_waitcnt vmcnt(0)
	ds_write_b128 v165, v[138:141] offset:30720
	s_waitcnt lgkmcnt(0)
	s_barrier
; __device__ __forceinline__ float fexp2(float x) { return __builtin_amdgcn_exp2f(x); }
; template <int DQK, int KSB>
; __device__ __forceinline__ void attn_scores(LAS const unsigned char* Kt, const bf16x8 (&qf)[DQK / 16], f32x16 (&p)[2], int r32, int hi) {
;     ...
;     for (int ks = 0; ks < NK; ++ks) {
;         if (ks + 2 < NK) QK_LOAD(ks + 2);
;         p0 = MFMA32(kr[ks % 3][0], qf[ks], p0); p1 = MFMA32(kr[ks % 3][1], qf[ks], p1); SCHED_FENCE();
;     }
;     ...
;     p[0] = p0; p[1] = p1;
; }
; template <int DV, bool MASK>
; __device__ __forceinline__ void attn_softmax(f32x16 (&p)[2], f32x16 (&o)[DV / 32], float& m, float& l, float cs, int hi, int dq) {
;     if (MASK) { if (__builtin_amdgcn_readfirstlane(dq) != NO_MASK) {
; #pragma unroll
;         for (int kvb = 0; kvb < 2; ++kvb)
; #pragma unroll
;             for (int e = 0; e < 16; ++e) { const int rel = dq + 32 * kvb + (e & 3) + 8 * (e >> 2) + 4 * hi; if (rel > 128 || rel < -128) p[kvb][e] = -INFINITY; } } }
;     float mx;
;     {
;         float a0 = fmaxf(fmaxf(p[0][0], p[0][1]), p[0][2]), a1 = fmaxf(fmaxf(p[0][8], p[0][9]), p[0][10]), a2 = fmaxf(fmaxf(p[1][0], p[1][1]), p[1][2]), a3 = fmaxf(fmaxf(p[1][8], p[1][9]), p[1][10]);
;         a0 = fmaxf(fmaxf(a0, p[0][3]), p[0][4]); a1 = fmaxf(fmaxf(a1, p[0][11]), p[0][12]); a2 = fmaxf(fmaxf(a2, p[1][3]), p[1][4]); a3 = fmaxf(fmaxf(a3, p[1][11]), p[1][12]);
;         a0 = fmaxf(fmaxf(a0, p[0][5]), p[0][6]); a1 = fmaxf(fmaxf(a1, p[0][13]), p[0][14]); a2 = fmaxf(fmaxf(a2, p[1][5]), p[1][6]); a3 = fmaxf(fmaxf(a3, p[1][13]), p[1][14]);
;         a0 = fmaxf(a0, p[0][7]); a1 = fmaxf(a1, p[0][15]); a2 = fmaxf(a2, p[1][7]); a3 = fmaxf(a3, p[1][15]);
;         mx = fmaxf(fmaxf(a0, a1), fmaxf(a2, a3));
;         const auto rr = __builtin_amdgcn_permlane32_swap(__float_as_uint(mx), __float_as_uint(mx), false, false);
;         mx = fmaxf(__uint_as_float(rr[0]), __uint_as_float(rr[1])); }
;     const float mn = fmaxf(m, mx * cs);
;     if (__any(mn - m > ATT_THR)) {
;         const float alpha = fexp2(m - mn); m = mn; l *= alpha;
; #pragma unroll
;         for (int d = 0; d < DV / 32; ++d)
; #pragma unroll
;             for (int e = 0; e < 16; ++e) o[d][e] *= alpha;
;     }
;     float ls0 = 0.f, ls1 = 0.f, ls2 = 0.f, ls3 = 0.f;
; #pragma unroll
;     for (int kvb = 0; kvb < 2; ++kvb)
; #pragma unroll
;         for (int e = 0; e < 16; e += 4) {
	ds_read_b128 v[82:85], v145 offset:21504
	ds_read_b128 v[134:137], v145 offset:21536
	ds_read_b128 v[86:89], v145 offset:26112
	ds_read_b128 v[138:141], v145 offset:26144
	s_waitcnt lgkmcnt(3)
	v_mfma_f32_32x32x16_bf16 v[98:113], v[82:85], v[130:133], 0
	ds_read_b128 v[186:189], v145 offset:21568
	ds_read_b128 v[216:219], v145 offset:26176
	s_waitcnt lgkmcnt(3)
	v_mfma_f32_32x32x16_bf16 v[82:97], v[86:89], v[130:133], 0
	v_mfma_f32_32x32x16_bf16 v[98:113], v[134:137], v[126:129], v[98:113]
	ds_read_b128 v[130:133], v145 offset:21600
	ds_read_b128 v[134:137], v145 offset:26208
	s_waitcnt lgkmcnt(4)
	v_mfma_f32_32x32x16_bf16 v[82:97], v[138:141], v[126:129], v[82:97]
	s_waitcnt lgkmcnt(3)
	v_mfma_f32_32x32x16_bf16 v[98:113], v[186:189], v[122:125], v[98:113]
	s_waitcnt lgkmcnt(2)
	v_mfma_f32_32x32x16_bf16 v[82:97], v[216:219], v[122:125], v[82:97]
	s_waitcnt lgkmcnt(1)
	v_mfma_f32_32x32x16_bf16 v[98:113], v[130:133], v[118:121], v[98:113]
	s_waitcnt lgkmcnt(0)
	v_mfma_f32_32x32x16_bf16 v[82:97], v[134:137], v[118:121], v[82:97]
	s_nop 10
	v_max_f32_e32 v118, v98, v99
	v_max_f32_e32 v121, v90, v91
	v_max_f32_e32 v119, v106, v107
	v_max3_f32 v120, v82, v83, v84
	v_max3_f32 v121, v121, v92, v93
	v_max3_f32 v118, v118, v100, v101
	v_max3_f32 v119, v119, v108, v109
	v_max3_f32 v120, v120, v85, v86
	v_max3_f32 v121, v121, v94, v95
	v_max3_f32 v118, v118, v102, v103
	v_max3_f32 v119, v119, v110, v111
	v_max3_f32 v120, v120, v87, v88
	v_max3_f32 v121, v121, v96, v97
	v_max3_f32 v118, v118, v104, v105
	v_max3_f32 v119, v119, v112, v113
	v_max3_f32 v120, v120, v89, v121
	v_max3_f32 v118, v118, v119, v120
	v_mov_b32_e32 v119, v118
	s_nop 1
	v_permlane32_swap_b32_e32 v118, v119
	v_max_f32_e32 v118, v118, v119
	v_mul_f32_e32 v118, 0x3e38aa3b, v118
	s_nop 0
	v_max_f32_e32 v118, v148, v118
	v_sub_f32_e32 v119, v118, v148
	v_cmp_lt_f32_e32 vcc, s34, v119
	s_cbranch_vccz .LBB0_847
	v_sub_f32_e32 v119, v148, v118
	v_exp_f32_e32 v120, v119
	v_xor_b32_e32 v147, 0x80000000, v118
	v_mul_f32_e32 v151, v151, v120
	v_pk_mul_f32 v[64:65], v[64:65], v[120:121] op_sel_hi:[1,0]
	v_pk_mul_f32 v[62:63], v[62:63], v[120:121] op_sel_hi:[1,0]
	v_pk_mul_f32 v[60:61], v[60:61], v[120:121] op_sel_hi:[1,0]
	v_pk_mul_f32 v[58:59], v[58:59], v[120:121] op_sel_hi:[1,0]
	v_pk_mul_f32 v[56:57], v[56:57], v[120:121] op_sel_hi:[1,0]
	v_pk_mul_f32 v[54:55], v[54:55], v[120:121] op_sel_hi:[1,0]
	v_pk_mul_f32 v[52:53], v[52:53], v[120:121] op_sel_hi:[1,0]
	v_pk_mul_f32 v[50:51], v[50:51], v[120:121] op_sel_hi:[1,0]
	v_pk_mul_f32 v[16:17], v[16:17], v[120:121] op_sel_hi:[1,0]
	v_pk_mul_f32 v[14:15], v[14:15], v[120:121] op_sel_hi:[1,0]
	v_pk_mul_f32 v[12:13], v[12:13], v[120:121] op_sel_hi:[1,0]
	v_pk_mul_f32 v[10:11], v[10:11], v[120:121] op_sel_hi:[1,0]
	v_pk_mul_f32 v[8:9], v[8:9], v[120:121] op_sel_hi:[1,0]
	v_pk_mul_f32 v[6:7], v[6:7], v[120:121] op_sel_hi:[1,0]
	v_pk_mul_f32 v[4:5], v[4:5], v[120:121] op_sel_hi:[1,0]
	v_pk_mul_f32 v[2:3], v[2:3], v[120:121] op_sel_hi:[1,0]
.LBB0_847:
	v_add_f32_e32 v118, 0, v153
	v_add_f32_e32 v119, 0, v154
	v_add_f32_e32 v120, 0, v155
	v_add_f32_e32 v121, 0, v162
	v_add_f32_e32 v118, v163, v118
	v_add_f32_e32 v119, v164, v119
	v_add_f32_e32 v120, v166, v120
	v_add_f32_e32 v121, v167, v121
	v_add_f32_e32 v118, v168, v118
	v_add_f32_e32 v119, v169, v119
	v_add_f32_e32 v120, v181, v120
	v_add_f32_e32 v121, v182, v121
	v_add_f32_e32 v118, v183, v118
	v_add_f32_e32 v119, v196, v119
	v_add_f32_e32 v120, v197, v120
	v_add_f32_e32 v121, v198, v121
	v_add_f32_e32 v118, v199, v118
	v_add_f32_e32 v119, v200, v119
	v_add_f32_e32 v120, v201, v120
	v_add_f32_e32 v121, v202, v121
	v_add_f32_e32 v118, v203, v118
	v_add_f32_e32 v119, v204, v119
	v_add_f32_e32 v120, v205, v120
	v_add_f32_e32 v121, v206, v121
	v_add_f32_e32 v118, v207, v118
	v_add_f32_e32 v119, v208, v119
	v_add_f32_e32 v120, v209, v120
	v_add_f32_e32 v121, v210, v121
	v_add_f32_e32 v118, v211, v118
	v_add_f32_e32 v119, v212, v119
	v_add_f32_e32 v120, v213, v120
	v_add_f32_e32 v121, v214, v121
	v_add_f32_e32 v118, v118, v119
	v_add_f32_e32 v119, v120, v121
	v_fmamk_f32 v98, v98, 0x3e38aa3b, v147
	v_add_f32_e32 v118, v118, v119
	v_exp_f32_e32 v119, v98
	v_fmamk_f32 v98, v99, 0x3e38aa3b, v147
	v_exp_f32_e32 v120, v98
	v_fmamk_f32 v98, v100, 0x3e38aa3b, v147
	v_fmamk_f32 v82, v82, 0x3e38aa3b, v147
	v_exp_f32_e32 v121, v98
	v_fmamk_f32 v98, v101, 0x3e38aa3b, v147
	v_exp_f32_e32 v135, v82
	v_fmamk_f32 v82, v83, 0x3e38aa3b, v147
	v_exp_f32_e32 v122, v98
	v_fmamk_f32 v98, v102, 0x3e38aa3b, v147
	v_exp_f32_e32 v136, v82
	v_fmamk_f32 v82, v84, 0x3e38aa3b, v147
	v_exp_f32_e32 v123, v98
	v_fmamk_f32 v98, v103, 0x3e38aa3b, v147
	v_exp_f32_e32 v137, v82
	v_fmamk_f32 v82, v85, 0x3e38aa3b, v147
	v_exp_f32_e32 v124, v98
	v_fmamk_f32 v98, v104, 0x3e38aa3b, v147
	v_exp_f32_e32 v138, v82
	v_fmamk_f32 v82, v86, 0x3e38aa3b, v147
	v_exp_f32_e32 v125, v98
	v_fmamk_f32 v98, v105, 0x3e38aa3b, v147
	v_exp_f32_e32 v139, v82
	v_fmamk_f32 v82, v87, 0x3e38aa3b, v147
	v_exp_f32_e32 v126, v98
	v_fmamk_f32 v98, v106, 0x3e38aa3b, v147
	v_exp_f32_e32 v140, v82
	v_fmamk_f32 v82, v88, 0x3e38aa3b, v147
	v_exp_f32_e32 v127, v98
	v_fmamk_f32 v98, v107, 0x3e38aa3b, v147
	v_exp_f32_e32 v141, v82
	v_fmamk_f32 v82, v89, 0x3e38aa3b, v147
	v_exp_f32_e32 v128, v98
	v_fmamk_f32 v98, v108, 0x3e38aa3b, v147
	v_exp_f32_e32 v148, v82
	v_fmamk_f32 v82, v90, 0x3e38aa3b, v147
	v_add_f32_e32 v118, v152, v118
	v_exp_f32_e32 v129, v98
	v_fmamk_f32 v98, v109, 0x3e38aa3b, v147
	v_exp_f32_e32 v152, v82
	v_fmamk_f32 v82, v91, 0x3e38aa3b, v147
	v_exp_f32_e32 v130, v98
	v_fmamk_f32 v98, v110, 0x3e38aa3b, v147
	v_exp_f32_e32 v153, v82
	v_fmamk_f32 v82, v92, 0x3e38aa3b, v147
	v_exp_f32_e32 v131, v98
	v_fmamk_f32 v98, v111, 0x3e38aa3b, v147
	v_exp_f32_e32 v154, v82
	v_fmamk_f32 v82, v93, 0x3e38aa3b, v147
	v_exp_f32_e32 v132, v98
	v_fmamk_f32 v98, v112, 0x3e38aa3b, v147
	v_exp_f32_e32 v155, v82
	v_fmamk_f32 v82, v94, 0x3e38aa3b, v147
	v_exp_f32_e32 v133, v98
	v_fmamk_f32 v98, v113, 0x3e38aa3b, v147
	v_exp_f32_e32 v162, v82
	v_fmamk_f32 v82, v95, 0x3e38aa3b, v147
	v_exp_f32_e32 v134, v98
	v_exp_f32_e32 v163, v82
	v_fmamk_f32 v82, v96, 0x3e38aa3b, v147
	v_fmac_f32_e32 v147, 0x3e38aa3b, v97
	ds_read_b64_tr_b16 v[94:95], v179 offset:30720
	ds_read_b64_tr_b16 v[96:97], v179 offset:32256
	ds_read_b64_tr_b16 v[100:101], v179 offset:32320
	ds_read_b64_tr_b16 v[98:99], v179 offset:30784
	v_exp_f32_e32 v164, v82
	v_exp_f32_e32 v166, v147
	v_cvt_pk_bf16_f32 v82, v119, v120
	v_cvt_pk_bf16_f32 v83, v121, v122
	v_cvt_pk_bf16_f32 v84, v123, v124
	v_cvt_pk_bf16_f32 v85, v125, v126
	v_cvt_pk_bf16_f32 v86, v127, v128
	v_cvt_pk_bf16_f32 v87, v129, v130
	v_cvt_pk_bf16_f32 v88, v131, v132
	v_cvt_pk_bf16_f32 v89, v133, v134
	v_cvt_pk_bf16_f32 v90, v135, v136
	v_cvt_pk_bf16_f32 v91, v137, v138
	v_cvt_pk_bf16_f32 v92, v139, v140
	v_cvt_pk_bf16_f32 v93, v141, v148
	v_cvt_pk_bf16_f32 v102, v152, v153
	v_cvt_pk_bf16_f32 v103, v154, v155
	v_cvt_pk_bf16_f32 v104, v162, v163
	v_cvt_pk_bf16_f32 v105, v164, v166
	s_waitcnt lgkmcnt(2)
; template <int DQK, int KSB>
; __device__ __forceinline__ void attn_scores(LAS const unsigned char* Kt, const bf16x8 (&qf)[DQK / 16], f32x16 (&p)[2], int r32, int hi) {
;     ...
;     for (int ks = 0; ks < NK; ++ks) {
;         if (ks + 2 < NK) QK_LOAD(ks + 2);
;         p0 = MFMA32(kr[ks % 3][0], qf[ks], p0); p1 = MFMA32(kr[ks % 3][1], qf[ks], p1); SCHED_FENCE();
;     }
;     ...
;     p[0] = p0; p[1] = p1;
; }
; template <int DV, bool MASK>
; __device__ __forceinline__ void attn_softmax(f32x16 (&p)[2], f32x16 (&o)[DV / 32], float& m, float& l, float cs, int hi, int dq) {
;     if (MASK) { if (__builtin_amdgcn_readfirstlane(dq) != NO_MASK) {
; #pragma unroll
;         for (int kvb = 0; kvb < 2; ++kvb)
; #pragma unroll
;             for (int e = 0; e < 16; ++e) { const int rel = dq + 32 * kvb + (e & 3) + 8 * (e >> 2) + 4 * hi; if (rel > 128 || rel < -128) p[kvb][e] = -INFINITY; } } }
;     float mx;
;     {
;         float a0 = fmaxf(fmaxf(p[0][0], p[0][1]), p[0][2]), a1 = fmaxf(fmaxf(p[0][8], p[0][9]), p[0][10]), a2 = fmaxf(fmaxf(p[1][0], p[1][1]), p[1][2]), a3 = fmaxf(fmaxf(p[1][8], p[1][9]), p[1][10]);
;         a0 = fmaxf(fmaxf(a0, p[0][3]), p[0][4]); a1 = fmaxf(fmaxf(a1, p[0][11]), p[0][12]); a2 = fmaxf(fmaxf(a2, p[1][3]), p[1][4]); a3 = fmaxf(fmaxf(a3, p[1][11]), p[1][12]);
;         a0 = fmaxf(fmaxf(a0, p[0][5]), p[0][6]); a1 = fmaxf(fmaxf(a1, p[0][13]), p[0][14]); a2 = fmaxf(fmaxf(a2, p[1][5]), p[1][6]); a3 = fmaxf(fmaxf(a3, p[1][13]), p[1][14]);
;         a0 = fmaxf(a0, p[0][7]); a1 = fmaxf(a1, p[0][15]); a2 = fmaxf(a2, p[1][7]); a3 = fmaxf(a3, p[1][15]);
;         mx = fmaxf(fmaxf(a0, a1), fmaxf(a2, a3));
;         const auto rr = __builtin_amdgcn_permlane32_swap(__float_as_uint(mx), __float_as_uint(mx), false, false);
;         mx = fmaxf(__uint_as_float(rr[0]), __uint_as_float(rr[1])); }
;     const float mn = fmaxf(m, mx * cs);
;     if (__any(mn - m > ATT_THR)) {
;         const float alpha = fexp2(m - mn); m = mn; l *= alpha;
; #pragma unroll
;         for (int d = 0; d < DV / 32; ++d)
; #pragma unroll
;             for (int e = 0; e < 16; ++e) o[d][e] *= alpha;
;     }
; template <int DV, int VRB>
; __device__ __forceinline__ void attn_pv(LAS const unsigned char* Vt, const f32x16 (&p)[2], f32x16 (&o)[DV / 32], int vtb) {
;     ...
;     PV_LOAD(va, 0); SCHED_FENCE();
;     PV_LOAD(vbq, 1); PV_MMA(va, 0); SCHED_FENCE();
	v_mfma_f32_32x32x16_bf16 v[50:65], v[94:97], v[82:85], v[50:65]
	ds_read_b64_tr_b16 v[94:95], v179 offset:33792
	ds_read_b64_tr_b16 v[96:97], v179 offset:35328
	ds_read_b64_tr_b16 v[108:109], v179 offset:35392
	ds_read_b64_tr_b16 v[106:107], v179 offset:33856
	s_waitcnt lgkmcnt(4)
	v_mfma_f32_32x32x16_bf16 v[2:17], v[98:101], v[82:85], v[2:17]
	s_waitcnt lgkmcnt(2)
	v_mfma_f32_32x32x16_bf16 v[50:65], v[94:97], v[86:89], v[50:65]
	ds_read_b64_tr_b16 v[82:83], v179 offset:36864
	ds_read_b64_tr_b16 v[84:85], v179 offset:38400
	ds_read_b64_tr_b16 v[96:97], v179 offset:38464
	ds_read_b64_tr_b16 v[94:95], v179 offset:36928
	s_waitcnt lgkmcnt(4)
	v_mfma_f32_32x32x16_bf16 v[2:17], v[106:109], v[86:89], v[2:17]
	s_waitcnt lgkmcnt(2)
	v_mfma_f32_32x32x16_bf16 v[50:65], v[82:85], v[90:93], v[50:65]
	ds_read_b64_tr_b16 v[82:83], v179 offset:39936
	ds_read_b64_tr_b16 v[84:85], v179 offset:41472
	ds_read_b64_tr_b16 v[88:89], v179 offset:41536
	ds_read_b64_tr_b16 v[86:87], v179 offset:40000
	s_waitcnt lgkmcnt(4)
	v_mfma_f32_32x32x16_bf16 v[2:17], v[94:97], v[90:93], v[2:17]
	s_waitcnt lgkmcnt(2)
	v_mfma_f32_32x32x16_bf16 v[50:65], v[82:85], v[102:105], v[50:65]
	s_waitcnt lgkmcnt(0)
	v_mfma_f32_32x32x16_bf16 v[2:17], v[86:89], v[102:105], v[2:17]
	ds_read_b128 v[82:85], v145 offset:21504
	ds_read_b128 v[186:189], v145 offset:21536
	ds_read_b128 v[86:89], v145 offset:26112
	ds_read_b128 v[196:199], v145 offset:26144
	s_waitcnt lgkmcnt(3)
	v_mfma_f32_32x32x16_bf16 v[98:113], v[82:85], v[114:117], 0
	ds_read_b128 v[200:203], v145 offset:21568
	ds_read_b128 v[204:207], v145 offset:26176
	s_waitcnt lgkmcnt(3)
	v_mfma_f32_32x32x16_bf16 v[82:97], v[86:89], v[114:117], 0
	v_mfma_f32_32x32x16_bf16 v[98:113], v[186:189], v[26:29], v[98:113]
	ds_read_b128 v[114:117], v145 offset:21600
	ds_read_b128 v[186:189], v145 offset:26208
	s_waitcnt lgkmcnt(4)
	v_mfma_f32_32x32x16_bf16 v[82:97], v[196:199], v[26:29], v[82:97]
	s_waitcnt lgkmcnt(3)
	v_mfma_f32_32x32x16_bf16 v[98:113], v[200:203], v[22:25], v[98:113]
	s_waitcnt lgkmcnt(2)
	v_mfma_f32_32x32x16_bf16 v[82:97], v[204:207], v[22:25], v[82:97]
	s_waitcnt lgkmcnt(1)
	v_mfma_f32_32x32x16_bf16 v[98:113], v[114:117], v[18:21], v[98:113]
	s_waitcnt lgkmcnt(0)
	v_mfma_f32_32x32x16_bf16 v[82:97], v[186:189], v[18:21], v[82:97]
	s_nop 10
	v_max_f32_e32 v18, v98, v99
	v_max_f32_e32 v21, v90, v91
	v_max_f32_e32 v19, v106, v107
	v_max3_f32 v20, v82, v83, v84
	v_max3_f32 v21, v21, v92, v93
	v_max3_f32 v18, v18, v100, v101
	v_max3_f32 v19, v19, v108, v109
	v_max3_f32 v20, v20, v85, v86
	v_max3_f32 v21, v21, v94, v95
	v_max3_f32 v18, v18, v102, v103
	v_max3_f32 v19, v19, v110, v111
	v_max3_f32 v20, v20, v87, v88
	v_max3_f32 v21, v21, v96, v97
	v_max3_f32 v18, v18, v104, v105
	v_max3_f32 v19, v19, v112, v113
	v_max3_f32 v20, v20, v89, v21
	v_max3_f32 v18, v18, v19, v20
	v_mov_b32_e32 v19, v18
	s_nop 1
	v_permlane32_swap_b32_e32 v18, v19
	v_max_f32_e32 v18, v18, v19
	v_mul_f32_e32 v18, 0x3e38aa3b, v18
	s_nop 0
	v_max_f32_e32 v18, v149, v18
	v_sub_f32_e32 v19, v18, v149
	v_cmp_lt_f32_e32 vcc, s34, v19
	s_cbranch_vccz .LBB0_849
	v_sub_f32_e32 v19, v149, v18
	v_exp_f32_e32 v20, v19
	v_xor_b32_e32 v150, 0x80000000, v18
	v_mul_f32_e32 v118, v118, v20
	v_pk_mul_f32 v[80:81], v[80:81], v[20:21] op_sel_hi:[1,0]
	v_pk_mul_f32 v[78:79], v[78:79], v[20:21] op_sel_hi:[1,0]
	v_pk_mul_f32 v[76:77], v[76:77], v[20:21] op_sel_hi:[1,0]
	v_pk_mul_f32 v[74:75], v[74:75], v[20:21] op_sel_hi:[1,0]
	v_pk_mul_f32 v[72:73], v[72:73], v[20:21] op_sel_hi:[1,0]
	v_pk_mul_f32 v[70:71], v[70:71], v[20:21] op_sel_hi:[1,0]
	v_pk_mul_f32 v[68:69], v[68:69], v[20:21] op_sel_hi:[1,0]
	v_pk_mul_f32 v[66:67], v[66:67], v[20:21] op_sel_hi:[1,0]
	v_pk_mul_f32 v[48:49], v[48:49], v[20:21] op_sel_hi:[1,0]
	v_pk_mul_f32 v[46:47], v[46:47], v[20:21] op_sel_hi:[1,0]
	v_pk_mul_f32 v[44:45], v[44:45], v[20:21] op_sel_hi:[1,0]
	v_pk_mul_f32 v[42:43], v[42:43], v[20:21] op_sel_hi:[1,0]
	v_pk_mul_f32 v[40:41], v[40:41], v[20:21] op_sel_hi:[1,0]
	v_pk_mul_f32 v[38:39], v[38:39], v[20:21] op_sel_hi:[1,0]
	v_pk_mul_f32 v[36:37], v[36:37], v[20:21] op_sel_hi:[1,0]
	v_pk_mul_f32 v[34:35], v[34:35], v[20:21] op_sel_hi:[1,0]

; __device__ __forceinline__ float fexp2(float x) { return __builtin_amdgcn_exp2f(x); }
; template <int DV, bool MASK>
; __device__ __forceinline__ void attn_softmax(f32x16 (&p)[2], f32x16 (&o)[DV / 32], float& m, float& l, float cs, int hi, int dq) {
;     if (MASK) { if (__builtin_amdgcn_readfirstlane(dq) != NO_MASK) {
; #pragma unroll
;         for (int kvb = 0; kvb < 2; ++kvb)
; #pragma unroll
;             for (int e = 0; e < 16; ++e) { const int rel = dq + 32 * kvb + (e & 3) + 8 * (e >> 2) + 4 * hi; if (rel > 128 || rel < -128) p[kvb][e] = -INFINITY; } } }
;     float mx;
;     {
;         float a0 = fmaxf(fmaxf(p[0][0], p[0][1]), p[0][2]), a1 = fmaxf(fmaxf(p[0][8], p[0][9]), p[0][10]), a2 = fmaxf(fmaxf(p[1][0], p[1][1]), p[1][2]), a3 = fmaxf(fmaxf(p[1][8], p[1][9]), p[1][10]);
;         a0 = fmaxf(fmaxf(a0, p[0][3]), p[0][4]); a1 = fmaxf(fmaxf(a1, p[0][11]), p[0][12]); a2 = fmaxf(fmaxf(a2, p[1][3]), p[1][4]); a3 = fmaxf(fmaxf(a3, p[1][11]), p[1][12]);
;         a0 = fmaxf(fmaxf(a0, p[0][5]), p[0][6]); a1 = fmaxf(fmaxf(a1, p[0][13]), p[0][14]); a2 = fmaxf(fmaxf(a2, p[1][5]), p[1][6]); a3 = fmaxf(fmaxf(a3, p[1][13]), p[1][14]);
;         a0 = fmaxf(a0, p[0][7]); a1 = fmaxf(a1, p[0][15]); a2 = fmaxf(a2, p[1][7]); a3 = fmaxf(a3, p[1][15]);
;         mx = fmaxf(fmaxf(a0, a1), fmaxf(a2, a3));
;         const auto rr = __builtin_amdgcn_permlane32_swap(__float_as_uint(mx), __float_as_uint(mx), false, false);
;         mx = fmaxf(__uint_as_float(rr[0]), __uint_as_float(rr[1])); }
;     const float mn = fmaxf(m, mx * cs);
;     if (__any(mn - m > ATT_THR)) {
;         const float alpha = fexp2(m - mn); m = mn; l *= alpha;
; #pragma unroll
;         for (int d = 0; d < DV / 32; ++d)
; #pragma unroll
;             for (int e = 0; e < 16; ++e) o[d][e] *= alpha;
;     }
.LBB0_859:
	s_nop 6
	v_max_f32_e32 v35, v113, v113
	v_max_f32_e32 v37, v112, v112
	v_max_f32_e32 v39, v105, v105
	v_max_f32_e32 v40, v104, v104
	v_max_f32_e32 v35, v37, v35
	v_max_f32_e32 v37, v121, v121
	v_max_f32_e32 v38, v120, v120
	v_max_f32_e32 v39, v40, v39
	v_max_f32_e32 v37, v38, v37
	v_max3_f32 v38, v96, v97, v98
	v_max3_f32 v39, v39, v106, v107
	v_max3_f32 v35, v35, v114, v115
	v_max3_f32 v37, v37, v122, v123
	v_max3_f32 v38, v38, v99, v100
	v_max3_f32 v39, v39, v108, v109
	v_max3_f32 v35, v35, v116, v117
	v_max3_f32 v37, v37, v124, v125
	v_max3_f32 v38, v38, v101, v102
	v_max3_f32 v39, v39, v110, v111
	v_max3_f32 v35, v35, v118, v119
	v_max3_f32 v37, v37, v126, v127
	v_max3_f32 v38, v38, v103, v39
	v_max3_f32 v35, v35, v37, v38
	v_mov_b32_e32 v37, v35
	s_nop 1
	v_permlane32_swap_b32_e32 v35, v37
	v_max_f32_e32 v35, v35, v37
	v_mul_f32_e32 v35, 0x3e38aa3b, v35
	s_nop 0
	v_max_f32_e32 v35, v36, v35
	v_sub_f32_e32 v37, v35, v36
	v_cmp_lt_f32_e32 vcc, s34, v37
	s_cbranch_vccz .LBB0_861
	v_sub_f32_e32 v36, v36, v35
	v_exp_f32_e32 v36, v36
	s_nop 0
	v_mul_f32_e32 v34, v34, v36
	v_pk_mul_f32 v[94:95], v[94:95], v[36:37] op_sel_hi:[1,0]
	v_pk_mul_f32 v[92:93], v[92:93], v[36:37] op_sel_hi:[1,0]
	v_pk_mul_f32 v[90:91], v[90:91], v[36:37] op_sel_hi:[1,0]
	v_pk_mul_f32 v[88:89], v[88:89], v[36:37] op_sel_hi:[1,0]
	v_pk_mul_f32 v[86:87], v[86:87], v[36:37] op_sel_hi:[1,0]
	v_pk_mul_f32 v[84:85], v[84:85], v[36:37] op_sel_hi:[1,0]
	v_pk_mul_f32 v[82:83], v[82:83], v[36:37] op_sel_hi:[1,0]
	v_pk_mul_f32 v[80:81], v[80:81], v[36:37] op_sel_hi:[1,0]
	v_pk_mul_f32 v[78:79], v[78:79], v[36:37] op_sel_hi:[1,0]
	v_pk_mul_f32 v[76:77], v[76:77], v[36:37] op_sel_hi:[1,0]
	v_pk_mul_f32 v[74:75], v[74:75], v[36:37] op_sel_hi:[1,0]
	v_pk_mul_f32 v[72:73], v[72:73], v[36:37] op_sel_hi:[1,0]
	v_pk_mul_f32 v[70:71], v[70:71], v[36:37] op_sel_hi:[1,0]
	v_pk_mul_f32 v[68:69], v[68:69], v[36:37] op_sel_hi:[1,0]
	v_pk_mul_f32 v[66:67], v[66:67], v[36:37] op_sel_hi:[1,0]
	v_pk_mul_f32 v[64:65], v[64:65], v[36:37] op_sel_hi:[1,0]
	s_branch .LBB0_862

; __device__ __forceinline__ float fexp(float x) { return __builtin_amdgcn_exp2f(x * LOG2E); }
; __device__ __forceinline__ float logsigf_(float x) { return fminf(x, 0.f) - log1pf(expf(-fabsf(x))); }
; __device__ __forceinline__ float scan_max(float v, int dir, int lane) {
; #pragma unroll
;     for (int o = 1; o < 64; o <<= 1) { const float t = dir == 0 ? __shfl_up(v, o) : __shfl_down(v, o); const bool ok = dir == 0 ? (lane >= o) : (lane + o < 64); if (ok) v = fmaxf(v, t); }
;     return v;
; __device__ __forceinline__ void mlstm_c_phase(int u_first, int G, bool skip_ctx, const bf16* Z, const float* GATES, const float* gbias, const float* gh  , const bf16* DC, const float* DN, const float* SC,
;                                               bf16* Y, LAS unsigned char* L, int tid) {
;     ...
;         const float bs = scan_sum(logsigf_(pfp), dir, lane);
;         const float u = pig - bs, pm = scan_max(u, dir, lane), m_in = pmin;
;         const float mt = bs + fmaxf(m_in, pm);
;         bq[lane] = bs - mt; uu[lane] = u; iwv[lane] = fexp(bs + m_in - mt); emt[lane] = fexp(-mt); nin[lane] = pnin;
.LBB0_914:
	s_or_b64 exec, exec, s[26:27]
	v_cmp_eq_u32_e64 s[16:17], v63, v41
	s_waitcnt lgkmcnt(0)
	v_max_f32_e32 v41, v56, v56
	s_nop 0
	v_max_f32_e32 v41, v47, v41
	v_cndmask_b32_e64 v41, v41, v47, s[16:17]
	s_and_saveexec_b64 s[16:17], vcc
	s_xor_b64 s[26:27], exec, s[16:17]
	v_cmp_eq_u32_e64 s[16:17], 62, v40
	s_nop 1
	v_cndmask_b32_e64 v40, 2, 0, s[16:17]
	v_add_lshl_u32 v40, v40, v185, 2
	ds_bpermute_b32 v42, v40, v41
	s_andn2_saveexec_b64 s[26:27], s[26:27]
	s_cbranch_execz .LBB0_918
	v_cmp_lt_i32_e64 s[16:17], v44, v39
	s_nop 1
	v_cndmask_b32_e64 v40, v44, v185, s[16:17]
	v_lshlrev_b32_e32 v40, 2, v40
	s_waitcnt lgkmcnt(0)
	ds_bpermute_b32 v42, v40, v41
.LBB0_918:
	s_or_b64 exec, exec, s[26:27]
	s_waitcnt lgkmcnt(0)
	v_max_f32_e32 v40, v42, v42
	s_nop 0
	v_max_f32_e32 v40, v41, v40
	v_cndmask_b32_e64 v40, v41, v40, s[4:5]
	s_and_saveexec_b64 s[4:5], vcc
	s_xor_b64 s[16:17], exec, s[4:5]
	v_cmp_eq_u32_e64 s[4:5], 60, v43
	s_nop 1
	v_cndmask_b32_e64 v41, 4, 0, s[4:5]
	v_add_lshl_u32 v41, v41, v185, 2
	ds_bpermute_b32 v41, v41, v40
	s_andn2_saveexec_b64 s[16:17], s[16:17]
	s_cbranch_execz .LBB0_922
	v_cmp_lt_i32_e64 s[4:5], v46, v39
	s_waitcnt lgkmcnt(0)
	s_nop 0
	v_cndmask_b32_e64 v41, v46, v185, s[4:5]
	v_lshlrev_b32_e32 v41, 2, v41
	ds_bpermute_b32 v41, v41, v40
.LBB0_922:
	s_or_b64 exec, exec, s[16:17]
	s_waitcnt lgkmcnt(0)
	v_max_f32_e32 v41, v41, v41
	s_nop 0
	v_max_f32_e32 v41, v40, v41
	v_cndmask_b32_e64 v40, v40, v41, s[8:9]
	s_and_saveexec_b64 s[4:5], vcc
	s_xor_b64 s[8:9], exec, s[4:5]
	v_cmp_eq_u32_e64 s[4:5], 56, v45
	s_nop 1
	v_cndmask_b32_e64 v41, 8, 0, s[4:5]
	v_add_lshl_u32 v41, v41, v185, 2
	ds_bpermute_b32 v41, v41, v40
	s_andn2_saveexec_b64 s[8:9], s[8:9]
	s_cbranch_execz .LBB0_926
	v_cmp_lt_i32_e64 s[4:5], v50, v39
	s_waitcnt lgkmcnt(0)
	s_nop 0
	v_cndmask_b32_e64 v41, v50, v185, s[4:5]
	v_lshlrev_b32_e32 v41, 2, v41
	ds_bpermute_b32 v41, v41, v40
.LBB0_926:
	s_or_b64 exec, exec, s[8:9]
	s_waitcnt lgkmcnt(0)
	v_max_f32_e32 v41, v41, v41
	s_nop 0
	v_max_f32_e32 v41, v40, v41
	v_cndmask_b32_e64 v40, v40, v41, s[10:11]
	s_and_saveexec_b64 s[4:5], vcc
	s_xor_b64 s[8:9], exec, s[4:5]
	v_cmp_eq_u32_e64 s[4:5], 48, v49
	s_nop 1
	v_cndmask_b32_e64 v41, 16, 0, s[4:5]
	v_add_lshl_u32 v41, v41, v185, 2
	ds_bpermute_b32 v41, v41, v40
	s_andn2_saveexec_b64 s[8:9], s[8:9]
	s_cbranch_execz .LBB0_930
	v_cmp_lt_i32_e64 s[4:5], v52, v39
	s_waitcnt lgkmcnt(0)
	s_nop 0
	v_cndmask_b32_e64 v41, v52, v185, s[4:5]
	v_lshlrev_b32_e32 v41, 2, v41
	ds_bpermute_b32 v41, v41, v40
.LBB0_930:
	s_or_b64 exec, exec, s[8:9]
	s_waitcnt lgkmcnt(0)
	v_max_f32_e32 v41, v41, v41
	s_nop 0
	v_max_f32_e32 v41, v40, v41
	v_cndmask_b32_e64 v40, v40, v41, s[14:15]
	s_and_saveexec_b64 s[4:5], vcc
	s_xor_b64 s[4:5], exec, s[4:5]
	ds_bpermute_b32 v41, v51, v40
	s_andn2_saveexec_b64 s[4:5], s[4:5]
	s_cbranch_execz .LBB0_934
	v_cmp_lt_i32_e32 vcc, v53, v39
	s_nop 1
	v_cndmask_b32_e32 v39, v53, v185, vcc
	v_lshlrev_b32_e32 v39, 2, v39
	s_waitcnt lgkmcnt(0)
	ds_bpermute_b32 v41, v39, v40
.LBB0_934:
	s_or_b64 exec, exec, s[4:5]
	s_waitcnt lgkmcnt(0)
	v_max_f32_e32 v39, v41, v41
	s_nop 0
	v_max_f32_e32 v39, v40, v39
	v_cndmask_b32_e64 v39, v40, v39, s[12:13]
	v_max_f32_e32 v39, v39, v39
	s_nop 0
	v_max_f32_e32 v39, v140, v39
	v_add_f32_e32 v39, v48, v39
	v_add_f32_e32 v40, v140, v48
	v_sub_f32_e32 v40, v40, v39
	v_mul_f32_e32 v40, 0x3fb8aa3b, v40
	v_mul_f32_e32 v41, 0xbfb8aa3b, v39
	v_exp_f32_e32 v40, v40
	v_exp_f32_e32 v41, v41
	v_sub_f32_e32 v39, v48, v39
	v_lshl_add_u32 v42, v63, 2, v147
	ds_write2st64_b32 v42, v39, v47 offset1:1
	ds_write2st64_b32 v42, v40, v41 offset0:2 offset1:3
	ds_write_b32 v42, v141 offset:1280

; template <int DQK, int KSB>
; __device__ __forceinline__ void attn_scores(LAS const unsigned char* Kt, const bf16x8 (&qf)[DQK / 16], f32x16 (&p)[2], int r32, int hi) {
;     constexpr int NK = DQK / 16;
;     LAS const unsigned char* kp = Kt + r32 * KSB + hi * 16;
;     f32x16 p0, p1;
; #pragma unroll
;     for (int e = 0; e < 16; ++e) { p0[e] = 0.f; p1[e] = 0.f; }
;     bf16x8 kr[3][2];
;     ...
;     QK_LOAD(0); QK_LOAD(1); SCHED_FENCE();
; #pragma unroll
;     for (int ks = 0; ks < NK; ++ks) {
;         if (ks + 2 < NK) QK_LOAD(ks + 2);
;         p0 = MFMA32(kr[ks % 3][0], qf[ks], p0); p1 = MFMA32(kr[ks % 3][1], qf[ks], p1); SCHED_FENCE();
;     }
;     ...
;     p[0] = p0; p[1] = p1;
; }
; template <int DV, bool MASK>
; __device__ __forceinline__ void attn_softmax(f32x16 (&p)[2], f32x16 (&o)[DV / 32], float& m, float& l, float cs, int hi, int dq) {
;     if (MASK) { if (__builtin_amdgcn_readfirstlane(dq) != NO_MASK) {
; #pragma unroll
;         for (int kvb = 0; kvb < 2; ++kvb)
; #pragma unroll
;             for (int e = 0; e < 16; ++e) { const int rel = dq + 32 * kvb + (e & 3) + 8 * (e >> 2) + 4 * hi; if (rel > 128 || rel < -128) p[kvb][e] = -INFINITY; } } }
;     float mx;
;     {
;         float a0 = fmaxf(fmaxf(p[0][0], p[0][1]), p[0][2]), a1 = fmaxf(fmaxf(p[0][8], p[0][9]), p[0][10]), a2 = fmaxf(fmaxf(p[1][0], p[1][1]), p[1][2]), a3 = fmaxf(fmaxf(p[1][8], p[1][9]), p[1][10]);
;         a0 = fmaxf(fmaxf(a0, p[0][3]), p[0][4]); a1 = fmaxf(fmaxf(a1, p[0][11]), p[0][12]); a2 = fmaxf(fmaxf(a2, p[1][3]), p[1][4]); a3 = fmaxf(fmaxf(a3, p[1][11]), p[1][12]);
;         a0 = fmaxf(fmaxf(a0, p[0][5]), p[0][6]); a1 = fmaxf(fmaxf(a1, p[0][13]), p[0][14]); a2 = fmaxf(fmaxf(a2, p[1][5]), p[1][6]); a3 = fmaxf(fmaxf(a3, p[1][13]), p[1][14]);
;         a0 = fmaxf(a0, p[0][7]); a1 = fmaxf(a1, p[0][15]); a2 = fmaxf(a2, p[1][7]); a3 = fmaxf(a3, p[1][15]);
;         mx = fmaxf(fmaxf(a0, a1), fmaxf(a2, a3));
;         const auto rr = __builtin_amdgcn_permlane32_swap(__float_as_uint(mx), __float_as_uint(mx), false, false);
;         mx = fmaxf(__uint_as_float(rr[0]), __uint_as_float(rr[1])); }
;     const float mn = fmaxf(m, mx * cs);
;     if (__any(mn - m > ATT_THR)) {
;         const float alpha = fexp2(m - mn); m = mn; l *= alpha;
; #pragma unroll
;         for (int d = 0; d < DV / 32; ++d)
; #pragma unroll
;             for (int e = 0; e < 16; ++e) o[d][e] *= alpha;
;     }
.LBB0_970:
	s_mul_i32 s12, s11, 0xb400
	s_add_i32 s12, s12, 0
	v_add3_u32 v32, s12, v207, v30
	ds_read_b128 v[34:37], v32
	ds_read_b128 v[38:41], v32 offset:32
	ds_read_b128 v[42:45], v32 offset:12800
	ds_read_b128 v[210:213], v32 offset:12832
	s_waitcnt lgkmcnt(3)
	v_mfma_f32_32x32x16_bf16 v[112:127], v[34:37], v[18:21], 0
	ds_read_b128 v[34:37], v32 offset:64
	ds_read_b128 v[214:217], v32 offset:12864
	s_waitcnt lgkmcnt(3)
	v_mfma_f32_32x32x16_bf16 v[96:111], v[42:45], v[18:21], 0
	v_mfma_f32_32x32x16_bf16 v[112:127], v[38:41], v[22:25], v[112:127]
	ds_read_b128 v[38:41], v32 offset:96
	ds_read_b128 v[42:45], v32 offset:12896
	s_waitcnt lgkmcnt(4)
	v_mfma_f32_32x32x16_bf16 v[96:111], v[210:213], v[22:25], v[96:111]
	s_waitcnt lgkmcnt(3)
	v_mfma_f32_32x32x16_bf16 v[112:127], v[34:37], v[26:29], v[112:127]
	ds_read_b128 v[34:37], v32 offset:128
	ds_read_b128 v[210:213], v32 offset:12928
	s_waitcnt lgkmcnt(4)
	v_mfma_f32_32x32x16_bf16 v[96:111], v[214:217], v[26:29], v[96:111]
	s_waitcnt lgkmcnt(3)
	v_mfma_f32_32x32x16_bf16 v[112:127], v[38:41], v[128:131], v[112:127]
	ds_read_b128 v[38:41], v32 offset:160
	ds_read_b128 v[214:217], v32 offset:12960
	s_waitcnt lgkmcnt(4)
	v_mfma_f32_32x32x16_bf16 v[96:111], v[42:45], v[128:131], v[96:111]
	s_waitcnt lgkmcnt(3)
	v_mfma_f32_32x32x16_bf16 v[112:127], v[34:37], v[132:135], v[112:127]
	ds_read_b128 v[34:37], v32 offset:192
	ds_read_b128 v[42:45], v32 offset:12992
	s_waitcnt lgkmcnt(4)
	v_mfma_f32_32x32x16_bf16 v[96:111], v[210:213], v[132:135], v[96:111]
	s_waitcnt lgkmcnt(3)
	v_mfma_f32_32x32x16_bf16 v[112:127], v[38:41], v[136:139], v[112:127]
	ds_read_b128 v[38:41], v32 offset:224
	ds_read_b128 v[210:213], v32 offset:13024
	s_waitcnt lgkmcnt(4)
	v_mfma_f32_32x32x16_bf16 v[96:111], v[214:217], v[136:139], v[96:111]
	s_waitcnt lgkmcnt(3)
	v_mfma_f32_32x32x16_bf16 v[112:127], v[34:37], v[140:143], v[112:127]
	ds_read_b128 v[34:37], v32 offset:256
	ds_read_b128 v[214:217], v32 offset:13056
	s_waitcnt lgkmcnt(4)
	v_mfma_f32_32x32x16_bf16 v[96:111], v[42:45], v[140:143], v[96:111]
	s_waitcnt lgkmcnt(3)
	v_mfma_f32_32x32x16_bf16 v[112:127], v[38:41], v[144:147], v[112:127]
	ds_read_b128 v[38:41], v32 offset:288
	ds_read_b128 v[42:45], v32 offset:13088
	s_waitcnt lgkmcnt(4)
	v_mfma_f32_32x32x16_bf16 v[96:111], v[210:213], v[144:147], v[96:111]
	s_waitcnt lgkmcnt(3)
	v_mfma_f32_32x32x16_bf16 v[112:127], v[34:37], v[152:155], v[112:127]
	ds_read_b128 v[34:37], v32 offset:320
	ds_read_b128 v[210:213], v32 offset:13120
	s_waitcnt lgkmcnt(4)
	v_mfma_f32_32x32x16_bf16 v[96:111], v[214:217], v[152:155], v[96:111]
	s_waitcnt lgkmcnt(3)
	v_mfma_f32_32x32x16_bf16 v[112:127], v[38:41], v[148:151], v[112:127]
	ds_read_b128 v[38:41], v32 offset:352
	ds_read_b128 v[214:217], v32 offset:13152
	s_waitcnt lgkmcnt(4)
	v_mfma_f32_32x32x16_bf16 v[96:111], v[42:45], v[148:151], v[96:111]
	s_waitcnt lgkmcnt(3)
	v_mfma_f32_32x32x16_bf16 v[112:127], v[34:37], v[160:163], v[112:127]
	s_waitcnt lgkmcnt(2)
	v_mfma_f32_32x32x16_bf16 v[96:111], v[210:213], v[160:163], v[96:111]
	s_waitcnt lgkmcnt(1)
	v_mfma_f32_32x32x16_bf16 v[112:127], v[38:41], v[156:159], v[112:127]
	s_waitcnt lgkmcnt(0)
	v_mfma_f32_32x32x16_bf16 v[96:111], v[214:217], v[156:159], v[96:111]
	s_nop 10
	v_max_f32_e32 v32, v112, v113
	v_max_f32_e32 v36, v104, v105
	v_max_f32_e32 v34, v120, v121
	v_max3_f32 v35, v96, v97, v98
	v_max3_f32 v36, v36, v106, v107
	v_max3_f32 v32, v32, v114, v115
	v_max3_f32 v34, v34, v122, v123
	v_max3_f32 v35, v35, v99, v100
	v_max3_f32 v36, v36, v108, v109
	v_max3_f32 v32, v32, v116, v117
	v_max3_f32 v34, v34, v124, v125
	v_max3_f32 v35, v35, v101, v102
	v_max3_f32 v36, v36, v110, v111
	v_max3_f32 v32, v32, v118, v119
	v_max3_f32 v34, v34, v126, v127
	v_max3_f32 v35, v35, v103, v36
	v_max3_f32 v32, v32, v34, v35
	v_mov_b32_e32 v34, v32
	s_nop 1
	v_permlane32_swap_b32_e32 v32, v34
	v_max_f32_e32 v32, v32, v34
	v_mul_f32_e32 v32, 0x3dd53b94, v32
	s_nop 0
	v_max_f32_e32 v32, v208, v32
	v_sub_f32_e32 v34, v32, v208
	v_cmp_lt_f32_e32 vcc, s34, v34
	s_barrier
	s_cbranch_vccz .LBB0_972
	v_sub_f32_e32 v34, v208, v32
	v_exp_f32_e32 v34, v34
	s_nop 0
	v_mul_f32_e32 v201, v201, v34
	v_pk_mul_f32 v[94:95], v[94:95], v[34:35] op_sel_hi:[1,0]
	v_pk_mul_f32 v[92:93], v[92:93], v[34:35] op_sel_hi:[1,0]
	v_pk_mul_f32 v[90:91], v[90:91], v[34:35] op_sel_hi:[1,0]
	v_pk_mul_f32 v[88:89], v[88:89], v[34:35] op_sel_hi:[1,0]
	v_pk_mul_f32 v[86:87], v[86:87], v[34:35] op_sel_hi:[1,0]
	v_pk_mul_f32 v[84:85], v[84:85], v[34:35] op_sel_hi:[1,0]
	v_pk_mul_f32 v[82:83], v[82:83], v[34:35] op_sel_hi:[1,0]
	v_pk_mul_f32 v[80:81], v[80:81], v[34:35] op_sel_hi:[1,0]
	v_pk_mul_f32 v[78:79], v[78:79], v[34:35] op_sel_hi:[1,0]
	v_pk_mul_f32 v[76:77], v[76:77], v[34:35] op_sel_hi:[1,0]
	v_pk_mul_f32 v[74:75], v[74:75], v[34:35] op_sel_hi:[1,0]
	v_pk_mul_f32 v[72:73], v[72:73], v[34:35] op_sel_hi:[1,0]
	v_pk_mul_f32 v[70:71], v[70:71], v[34:35] op_sel_hi:[1,0]
	v_pk_mul_f32 v[68:69], v[68:69], v[34:35] op_sel_hi:[1,0]
	v_pk_mul_f32 v[66:67], v[66:67], v[34:35] op_sel_hi:[1,0]
	v_pk_mul_f32 v[64:65], v[64:65], v[34:35] op_sel_hi:[1,0]
	v_pk_mul_f32 v[62:63], v[62:63], v[34:35] op_sel_hi:[1,0]
	v_pk_mul_f32 v[60:61], v[60:61], v[34:35] op_sel_hi:[1,0]
	v_pk_mul_f32 v[58:59], v[58:59], v[34:35] op_sel_hi:[1,0]
	v_pk_mul_f32 v[56:57], v[56:57], v[34:35] op_sel_hi:[1,0]
	v_pk_mul_f32 v[54:55], v[54:55], v[34:35] op_sel_hi:[1,0]
	v_pk_mul_f32 v[52:53], v[52:53], v[34:35] op_sel_hi:[1,0]
	v_pk_mul_f32 v[50:51], v[50:51], v[34:35] op_sel_hi:[1,0]
	v_pk_mul_f32 v[48:49], v[48:49], v[34:35] op_sel_hi:[1,0]
	v_pk_mul_f32 v[16:17], v[16:17], v[34:35] op_sel_hi:[1,0]
	v_pk_mul_f32 v[14:15], v[14:15], v[34:35] op_sel_hi:[1,0]
	v_pk_mul_f32 v[12:13], v[12:13], v[34:35] op_sel_hi:[1,0]
	v_pk_mul_f32 v[10:11], v[10:11], v[34:35] op_sel_hi:[1,0]
	v_pk_mul_f32 v[8:9], v[8:9], v[34:35] op_sel_hi:[1,0]
	v_pk_mul_f32 v[6:7], v[6:7], v[34:35] op_sel_hi:[1,0]
	v_pk_mul_f32 v[4:5], v[4:5], v[34:35] op_sel_hi:[1,0]
	v_pk_mul_f32 v[2:3], v[2:3], v[34:35] op_sel_hi:[1,0]
	s_branch .LBB0_973
